# conv-FFN epilogue: the two 8-byte halves of each lane's activation row segment stored as one 16-byte store
# baseline (speedup 1.0000x reference)
.LBB0_1701:
	s_or_b64 exec, exec, s[4:5]
	v_lshlrev_b64 v[140:141], 2, v[170:171]
	v_lshl_add_u64 v[172:173], s[38:39], 0, v[140:141]
	v_lshl_add_u64 v[190:191], s[84:85], 0, v[140:141]
	v_lshl_add_u64 v[174:175], s[40:41], 0, v[140:141]
	v_lshl_add_u64 v[192:193], s[86:87], 0, v[140:141]
	v_lshl_add_u64 v[196:197], s[90:91], 0, v[140:141]
	v_lshl_add_u64 v[198:199], s[94:95], 0, v[140:141]
	v_lshl_add_u64 v[188:189], s[82:83], 0, v[140:141]
	global_load_dwordx4 v[144:147], v[172:173], off
	global_load_dwordx4 v[148:151], v[188:189], off
	global_load_dwordx4 v[152:155], v[190:191], off
	global_load_dwordx4 v[156:159], v[174:175], off
	v_lshl_add_u64 v[194:195], s[88:89], 0, v[140:141]
	global_load_dwordx4 v[128:131], v[192:193], off
	global_load_dwordx4 v[132:135], v[194:195], off
	global_load_dwordx4 v[136:139], v[196:197], off
	global_load_dwordx4 v[140:143], v[198:199], off
	v_mov_b32_dpp v227, v124 row_mirror row_mask:0xf bank_mask:0xf bound_ctrl:1
	v_mov_b32_dpp v223, v116 row_mirror row_mask:0xf bank_mask:0xf bound_ctrl:1
	v_mov_b32_dpp v251, v120 row_mirror row_mask:0xf bank_mask:0xf bound_ctrl:1
	v_mov_b32_dpp v181, v112 row_mirror row_mask:0xf bank_mask:0xf bound_ctrl:1
	v_mov_b32_dpp v178, v124 row_shr:1 row_mask:0xf bank_mask:0xf bound_ctrl:1
	v_mov_b32_dpp v179, v124 row_shl:1 row_mask:0xf bank_mask:0xf bound_ctrl:1
	v_mov_b32_dpp v253, v120 row_shr:1 row_mask:0xf bank_mask:0xf bound_ctrl:1
	v_mov_b32_dpp v230, v120 row_shl:1 row_mask:0xf bank_mask:0xf bound_ctrl:1
	v_mov_b32_dpp v180, v125 row_mirror row_mask:0xf bank_mask:0xf bound_ctrl:1
	v_mov_b32_dpp v234, v117 row_mirror row_mask:0xf bank_mask:0xf bound_ctrl:1
	v_mov_b32_dpp v225, v121 row_mirror row_mask:0xf bank_mask:0xf bound_ctrl:1
	v_mov_b32_dpp v232, v113 row_mirror row_mask:0xf bank_mask:0xf bound_ctrl:1
	v_mov_b32_dpp v229, v125 row_shr:1 row_mask:0xf bank_mask:0xf bound_ctrl:1
	v_mov_b32_dpp v231, v125 row_shl:1 row_mask:0xf bank_mask:0xf bound_ctrl:1
	v_mov_b32_dpp v226, v121 row_shr:1 row_mask:0xf bank_mask:0xf bound_ctrl:1
	v_mov_b32_dpp v233, v121 row_shl:1 row_mask:0xf bank_mask:0xf bound_ctrl:1
	v_mov_b32_dpp v240, v126 row_mirror row_mask:0xf bank_mask:0xf bound_ctrl:1
	v_mov_b32_dpp v242, v118 row_mirror row_mask:0xf bank_mask:0xf bound_ctrl:1
	v_mov_b32_dpp v213, v122 row_mirror row_mask:0xf bank_mask:0xf bound_ctrl:1
	v_mov_b32_dpp v246, v114 row_mirror row_mask:0xf bank_mask:0xf bound_ctrl:1
	v_mov_b32_dpp v241, v126 row_shr:1 row_mask:0xf bank_mask:0xf bound_ctrl:1
	v_mov_b32_dpp v244, v126 row_shl:1 row_mask:0xf bank_mask:0xf bound_ctrl:1
	v_mov_b32_dpp v237, v122 row_shr:1 row_mask:0xf bank_mask:0xf bound_ctrl:1
	v_mov_b32_dpp v248, v122 row_shl:1 row_mask:0xf bank_mask:0xf bound_ctrl:1
	v_mov_b32_dpp v243, v127 row_mirror row_mask:0xf bank_mask:0xf bound_ctrl:1
	v_mov_b32_dpp v247, v119 row_mirror row_mask:0xf bank_mask:0xf bound_ctrl:1
	v_mov_b32_dpp v238, v123 row_mirror row_mask:0xf bank_mask:0xf bound_ctrl:1
	v_mov_b32_dpp v250, v115 row_mirror row_mask:0xf bank_mask:0xf bound_ctrl:1
	v_mov_b32_dpp v245, v127 row_shr:1 row_mask:0xf bank_mask:0xf bound_ctrl:1
	v_mov_b32_dpp v249, v127 row_shl:1 row_mask:0xf bank_mask:0xf bound_ctrl:1
	v_mov_b32_dpp v239, v123 row_shr:1 row_mask:0xf bank_mask:0xf bound_ctrl:1
	v_mov_b32_dpp v252, v123 row_shl:1 row_mask:0xf bank_mask:0xf bound_ctrl:1
	v_cmp_lt_i32_e64 s[4:5], 0, v209
	v_cmp_gt_i32_e64 s[6:7], 15, v209
	v_cmp_lt_i32_e32 vcc, 62, v209
	s_mov_b64 s[14:15], 0
	v_cmp_ne_u32_e64 s[10:11], 63, v209
	s_and_saveexec_b64 s[12:13], vcc
	s_xor_b64 s[12:13], exec, s[12:13]
	s_and_b64 s[14:15], s[10:11], exec
	s_andn2_saveexec_b64 s[12:13], s[12:13]
	s_andn2_b64 s[14:15], s[14:15], exec
	s_and_b64 s[16:17], s[8:9], exec
	s_or_b64 s[14:15], s[14:15], s[16:17]
	s_or_b64 exec, exec, s[12:13]
	v_cndmask_b32_e64 v208, v212, v208, s[4:5]
	v_cndmask_b32_e64 v210, v216, v210, s[6:7]
	s_and_saveexec_b64 s[12:13], s[14:15]
	s_cbranch_execz .LBB0_1707
	v_cndmask_b32_e64 v184, v223, v179, s[6:7]
	v_cndmask_b32_e64 v179, v180, v229, s[4:5]
	v_cndmask_b32_e64 v178, v227, v178, s[4:5]
	v_pk_mul_f32 v[178:179], v[208:209], v[178:179] op_sel_hi:[0,1]
	v_cndmask_b32_e64 v182, v181, v230, s[6:7]
	v_cndmask_b32_e64 v185, v234, v231, s[6:7]
	v_pk_mul_f32 v[230:231], v[124:125], v[206:207] op_sel_hi:[1,0]
	s_waitcnt vmcnt(4)
	v_pk_fma_f32 v[178:179], v[144:145], v[178:179], v[156:157]
	v_pk_mul_f32 v[180:181], v[210:211], v[184:185] op_sel_hi:[0,1]
	v_pk_fma_f32 v[178:179], v[230:231], v[148:149], v[178:179]
	v_cndmask_b32_e64 v185, v225, v226, s[4:5]
	v_pk_fma_f32 v[178:179], v[152:153], v[180:181], v[178:179]
	v_cndmask_b32_e64 v184, v251, v253, s[4:5]
	v_mul_f32_e32 v180, 0xbfb8aa3b, v178
	v_exp_f32_e32 v223, v180
	v_mul_f32_e32 v224, 0xbfb8aa3b, v179
	v_exp_f32_e32 v225, v224
	v_pk_mul_f32 v[184:185], v[208:209], v[184:185] op_sel_hi:[0,1]
	v_add_f32_e32 v223, 1.0, v223
	v_rcp_f32_e32 v224, v223
	v_add_f32_e32 v223, 1.0, v225
	v_rcp_f32_e32 v225, v223
	v_cndmask_b32_e64 v183, v232, v233, s[6:7]
	v_pk_mul_f32 v[180:181], v[120:121], v[206:207] op_sel_hi:[1,0]
	s_waitcnt vmcnt(0)
	v_pk_fma_f32 v[184:185], v[128:129], v[184:185], v[140:141]
	v_pk_mul_f32 v[178:179], v[178:179], v[224:225]
	v_cndmask_b32_e64 v225, v243, v245, s[4:5]
	v_cndmask_b32_e64 v224, v240, v241, s[4:5]
	v_pk_mul_f32 v[182:183], v[210:211], v[182:183] op_sel_hi:[0,1]
	v_pk_fma_f32 v[180:181], v[180:181], v[132:133], v[184:185]
	v_pk_mul_f32 v[224:225], v[208:209], v[224:225] op_sel_hi:[0,1]
	v_pk_fma_f32 v[180:181], v[136:137], v[182:183], v[180:181]
	v_cndmask_b32_e64 v183, v247, v249, s[6:7]
	v_cndmask_b32_e64 v182, v242, v244, s[6:7]
	v_pk_mul_f32 v[184:185], v[126:127], v[206:207] op_sel_hi:[1,0]
	v_pk_fma_f32 v[224:225], v[146:147], v[224:225], v[158:159]
	v_pk_mul_f32 v[182:183], v[210:211], v[182:183] op_sel_hi:[0,1]
	v_pk_fma_f32 v[184:185], v[184:185], v[150:151], v[224:225]
	v_cndmask_b32_e64 v224, v213, v237, s[4:5]
	v_pk_fma_f32 v[182:183], v[154:155], v[182:183], v[184:185]
	v_cndmask_b32_e64 v225, v238, v239, s[4:5]
	v_mul_f32_e32 v184, 0xbfb8aa3b, v182
	v_exp_f32_e32 v223, v184
	v_pk_mul_f32 v[224:225], v[208:209], v[224:225] op_sel_hi:[0,1]
	v_pk_mul_f32 v[178:179], v[180:181], v[178:179]
	v_cndmask_b32_e64 v181, v250, v252, s[6:7]
	v_add_f32_e32 v213, 1.0, v223
	v_mul_f32_e32 v223, 0xbfb8aa3b, v183
	v_exp_f32_e32 v223, v223
	v_rcp_f32_e32 v226, v213
	v_cndmask_b32_e64 v180, v246, v248, s[6:7]
	v_pk_mul_f32 v[184:185], v[122:123], v[206:207] op_sel_hi:[1,0]
	v_add_f32_e32 v213, 1.0, v223
	v_rcp_f32_e32 v227, v213
	v_pk_fma_f32 v[224:225], v[130:131], v[224:225], v[142:143]
	v_pk_mul_f32 v[180:181], v[210:211], v[180:181] op_sel_hi:[0,1]
	v_pk_fma_f32 v[184:185], v[184:185], v[134:135], v[224:225]
	v_pk_mul_f32 v[182:183], v[182:183], v[226:227]
	v_pk_fma_f32 v[180:181], v[138:139], v[180:181], v[184:185]
	v_cvt_pk_bf16_f32 v178, v178, v179
	v_pk_mul_f32 v[180:181], v[180:181], v[182:183]
	v_mov_b32_e32 v224, 0x1800
	v_cvt_pk_bf16_f32 v179, v180, v181
	v_mov_b64_e32 v[180:181], s[30:31]
	v_mad_i64_i32 v[180:181], s[14:15], v204, s1, v[180:181]
	v_lshl_add_u64 v[180:181], v[170:171], 1, v[180:181]
	v_mov_b32_e32 v248, v178
	v_mov_b32_e32 v249, v179
.LBB0_1707:
	s_or_b64 exec, exec, s[12:13]
	v_mov_b32_dpp v223, v124 row_mirror row_mask:0xf bank_mask:0xf bound_ctrl:1
	v_mov_b32_dpp v229, v108 row_mirror row_mask:0xf bank_mask:0xf bound_ctrl:1
	v_mov_b32_dpp v227, v120 row_mirror row_mask:0xf bank_mask:0xf bound_ctrl:1
	v_mov_b32_dpp v233, v104 row_mirror row_mask:0xf bank_mask:0xf bound_ctrl:1
	v_mov_b32_dpp v230, v116 row_shr:1 row_mask:0xf bank_mask:0xf bound_ctrl:1
	v_mov_b32_dpp v231, v116 row_shl:1 row_mask:0xf bank_mask:0xf bound_ctrl:1
	v_mov_b32_dpp v179, v112 row_shr:1 row_mask:0xf bank_mask:0xf bound_ctrl:1
	v_mov_b32_dpp v244, v112 row_shl:1 row_mask:0xf bank_mask:0xf bound_ctrl:1
	v_mov_b32_dpp v232, v125 row_mirror row_mask:0xf bank_mask:0xf bound_ctrl:1
	v_mov_b32_dpp v234, v109 row_mirror row_mask:0xf bank_mask:0xf bound_ctrl:1
	v_mov_b32_dpp v180, v121 row_mirror row_mask:0xf bank_mask:0xf bound_ctrl:1
	v_mov_b32_dpp v246, v105 row_mirror row_mask:0xf bank_mask:0xf bound_ctrl:1
	v_mov_b32_dpp v243, v117 row_shr:1 row_mask:0xf bank_mask:0xf bound_ctrl:1
	v_mov_b32_dpp v245, v117 row_shl:1 row_mask:0xf bank_mask:0xf bound_ctrl:1
	v_mov_b32_dpp v181, v113 row_shr:1 row_mask:0xf bank_mask:0xf bound_ctrl:1
	v_mov_b32_dpp v247, v113 row_shl:1 row_mask:0xf bank_mask:0xf bound_ctrl:1
	v_mov_b32_dpp v124, v126 row_mirror row_mask:0xf bank_mask:0xf bound_ctrl:1
	v_mov_b32_dpp v126, v110 row_mirror row_mask:0xf bank_mask:0xf bound_ctrl:1
	v_mov_b32_dpp v120, v122 row_mirror row_mask:0xf bank_mask:0xf bound_ctrl:1
	v_mov_b32_dpp v240, v106 row_mirror row_mask:0xf bank_mask:0xf bound_ctrl:1
	v_mov_b32_dpp v125, v118 row_shr:1 row_mask:0xf bank_mask:0xf bound_ctrl:1
	v_mov_b32_dpp v238, v118 row_shl:1 row_mask:0xf bank_mask:0xf bound_ctrl:1
	v_mov_b32_dpp v121, v114 row_shr:1 row_mask:0xf bank_mask:0xf bound_ctrl:1
	v_mov_b32_dpp v225, v114 row_shl:1 row_mask:0xf bank_mask:0xf bound_ctrl:1
	v_mov_b32_dpp v127, v127 row_mirror row_mask:0xf bank_mask:0xf bound_ctrl:1
	v_mov_b32_dpp v241, v111 row_mirror row_mask:0xf bank_mask:0xf bound_ctrl:1
	v_mov_b32_dpp v122, v123 row_mirror row_mask:0xf bank_mask:0xf bound_ctrl:1
	v_mov_b32_dpp v226, v107 row_mirror row_mask:0xf bank_mask:0xf bound_ctrl:1
	v_mov_b32_dpp v239, v119 row_shr:1 row_mask:0xf bank_mask:0xf bound_ctrl:1
	v_mov_b32_dpp v242, v119 row_shl:1 row_mask:0xf bank_mask:0xf bound_ctrl:1
	v_mov_b32_dpp v123, v115 row_shr:1 row_mask:0xf bank_mask:0xf bound_ctrl:1
	v_mov_b32_dpp v178, v115 row_shl:1 row_mask:0xf bank_mask:0xf bound_ctrl:1
	v_cmp_lt_i32_e32 vcc, 46, v209
	s_mov_b64 s[18:19], 0
	v_cmp_ne_u32_e64 s[12:13], 47, v209
	s_and_saveexec_b64 s[14:15], vcc
	s_xor_b64 s[14:15], exec, s[14:15]
	s_and_b64 s[18:19], s[12:13], exec
	s_or_saveexec_b64 s[16:17], s[14:15]
	v_cmp_ne_u32_e64 s[14:15], -16, v209
	s_xor_b64 exec, exec, s[16:17]
	s_andn2_b64 s[18:19], s[18:19], exec
	s_and_b64 s[20:21], s[14:15], exec
	s_or_b64 s[18:19], s[18:19], s[20:21]
	s_or_b64 exec, exec, s[16:17]
	v_add_u32_e32 v213, 16, v209
	v_cndmask_b32_e64 v212, v212, v214, s[4:5]
	v_cndmask_b32_e64 v214, v219, v215, s[6:7]
	v_add_u32_e32 v237, s42, v213
	s_and_saveexec_b64 s[16:17], s[18:19]
	s_cbranch_execz .LBB0_1713
	v_cndmask_b32_e64 v184, v229, v231, s[6:7]
	v_cndmask_b32_e64 v231, v232, v243, s[4:5]
	v_cndmask_b32_e64 v230, v223, v230, s[4:5]
	v_pk_mul_f32 v[230:231], v[212:213], v[230:231] op_sel_hi:[0,1]
	v_cndmask_b32_e64 v185, v234, v245, s[6:7]
	v_pk_mul_f32 v[228:229], v[116:117], v[202:203] op_sel_hi:[1,0]
	s_waitcnt vmcnt(4)
	v_pk_fma_f32 v[230:231], v[144:145], v[230:231], v[156:157]
	v_pk_mul_f32 v[184:185], v[214:215], v[184:185] op_sel_hi:[0,1]
	v_pk_fma_f32 v[228:229], v[228:229], v[148:149], v[230:231]
	v_cndmask_b32_e64 v181, v180, v181, s[4:5]
	v_pk_fma_f32 v[184:185], v[152:153], v[184:185], v[228:229]
	v_cndmask_b32_e64 v180, v227, v179, s[4:5]
	v_mul_f32_e32 v215, 0xbfb8aa3b, v184
	v_exp_f32_e32 v215, v215
	v_pk_mul_f32 v[180:181], v[212:213], v[180:181] op_sel_hi:[0,1]
	v_cndmask_b32_e64 v183, v246, v247, s[6:7]
	v_cndmask_b32_e64 v182, v233, v244, s[6:7]
	v_add_f32_e32 v179, 1.0, v215
	v_mul_f32_e32 v215, 0xbfb8aa3b, v185
	v_exp_f32_e32 v215, v215
	v_rcp_f32_e32 v230, v179
	v_pk_mul_f32 v[228:229], v[112:113], v[202:203] op_sel_hi:[1,0]
	s_waitcnt vmcnt(0)
	v_pk_fma_f32 v[180:181], v[128:129], v[180:181], v[140:141]
	v_add_f32_e32 v179, 1.0, v215
	v_rcp_f32_e32 v231, v179
	v_pk_mul_f32 v[182:183], v[214:215], v[182:183] op_sel_hi:[0,1]
	v_pk_fma_f32 v[180:181], v[228:229], v[132:133], v[180:181]
	v_cndmask_b32_e64 v127, v127, v239, s[4:5]
	v_pk_fma_f32 v[180:181], v[136:137], v[182:183], v[180:181]
	v_pk_mul_f32 v[182:183], v[184:185], v[230:231]
	v_pk_mul_f32 v[184:185], v[118:119], v[202:203] op_sel_hi:[1,0]
	v_pk_mul_f32 v[180:181], v[180:181], v[182:183]
	v_cndmask_b32_e64 v182, v126, v238, s[6:7]
	v_cndmask_b32_e64 v126, v124, v125, s[4:5]
	v_pk_mul_f32 v[126:127], v[212:213], v[126:127] op_sel_hi:[0,1]
	v_cndmask_b32_e64 v183, v241, v242, s[6:7]
	v_pk_fma_f32 v[126:127], v[146:147], v[126:127], v[158:159]
	v_pk_mul_f32 v[124:125], v[214:215], v[182:183] op_sel_hi:[0,1]
	v_pk_fma_f32 v[126:127], v[184:185], v[150:151], v[126:127]
	v_cndmask_b32_e64 v123, v122, v123, s[4:5]
	v_pk_fma_f32 v[124:125], v[154:155], v[124:125], v[126:127]
	v_cndmask_b32_e64 v122, v120, v121, s[4:5]
	v_mul_f32_e32 v126, 0xbfb8aa3b, v124
	v_mul_f32_e32 v121, 0xbfb8aa3b, v125
	v_exp_f32_e32 v182, v126
	v_exp_f32_e32 v121, v121
	v_pk_mul_f32 v[122:123], v[212:213], v[122:123] op_sel_hi:[0,1]
	v_cndmask_b32_e64 v179, v226, v178, s[6:7]
	v_add_f32_e32 v120, 1.0, v182
	v_add_f32_e32 v121, 1.0, v121
	v_rcp_f32_e32 v120, v120
	v_rcp_f32_e32 v121, v121
	v_cndmask_b32_e64 v178, v240, v225, s[6:7]
	v_pk_mul_f32 v[126:127], v[114:115], v[202:203] op_sel_hi:[1,0]
	v_pk_fma_f32 v[122:123], v[130:131], v[122:123], v[142:143]
	v_pk_mul_f32 v[178:179], v[214:215], v[178:179] op_sel_hi:[0,1]
	v_pk_fma_f32 v[122:123], v[126:127], v[134:135], v[122:123]
	v_pk_mul_f32 v[120:121], v[124:125], v[120:121]
	v_pk_fma_f32 v[122:123], v[138:139], v[178:179], v[122:123]
	s_nop 0
	v_pk_mul_f32 v[120:121], v[122:123], v[120:121]
	v_cvt_pk_bf16_f32 v122, v180, v181
	v_cvt_pk_bf16_f32 v123, v120, v121
	v_mov_b64_e32 v[120:121], s[30:31]
	v_mad_i64_i32 v[120:121], s[18:19], v237, s1, v[120:121]
	v_lshl_add_u64 v[120:121], v[170:171], 1, v[120:121]
	v_mov_b32_e32 v250, v122
	v_mov_b32_e32 v251, v123
.LBB0_1713:
	s_or_b64 exec, exec, s[16:17]
	v_mov_b32_dpp v223, v116 row_mirror row_mask:0xf bank_mask:0xf bound_ctrl:1
	v_mov_b32_dpp v225, v100 row_mirror row_mask:0xf bank_mask:0xf bound_ctrl:1
	v_mov_b32_dpp v127, v112 row_mirror row_mask:0xf bank_mask:0xf bound_ctrl:1
	v_mov_b32_dpp v230, v96 row_mirror row_mask:0xf bank_mask:0xf bound_ctrl:1
	v_mov_b32_dpp v226, v108 row_shr:1 row_mask:0xf bank_mask:0xf bound_ctrl:1
	v_mov_b32_dpp v227, v108 row_shl:1 row_mask:0xf bank_mask:0xf bound_ctrl:1
	v_mov_b32_dpp v179, v104 row_shr:1 row_mask:0xf bank_mask:0xf bound_ctrl:1
	v_mov_b32_dpp v233, v104 row_shl:1 row_mask:0xf bank_mask:0xf bound_ctrl:1
	v_mov_b32_dpp v229, v117 row_mirror row_mask:0xf bank_mask:0xf bound_ctrl:1
	v_mov_b32_dpp v231, v101 row_mirror row_mask:0xf bank_mask:0xf bound_ctrl:1
	v_mov_b32_dpp v180, v113 row_mirror row_mask:0xf bank_mask:0xf bound_ctrl:1
	v_mov_b32_dpp v239, v97 row_mirror row_mask:0xf bank_mask:0xf bound_ctrl:1
	v_mov_b32_dpp v232, v109 row_shr:1 row_mask:0xf bank_mask:0xf bound_ctrl:1
	v_mov_b32_dpp v234, v109 row_shl:1 row_mask:0xf bank_mask:0xf bound_ctrl:1
	v_mov_b32_dpp v181, v105 row_shr:1 row_mask:0xf bank_mask:0xf bound_ctrl:1
	v_mov_b32_dpp v240, v105 row_shl:1 row_mask:0xf bank_mask:0xf bound_ctrl:1
	v_mov_b32_dpp v116, v118 row_mirror row_mask:0xf bank_mask:0xf bound_ctrl:1
	v_mov_b32_dpp v118, v102 row_mirror row_mask:0xf bank_mask:0xf bound_ctrl:1
	v_mov_b32_dpp v112, v114 row_mirror row_mask:0xf bank_mask:0xf bound_ctrl:1
	v_mov_b32_dpp v122, v98 row_mirror row_mask:0xf bank_mask:0xf bound_ctrl:1
	v_mov_b32_dpp v117, v110 row_shr:1 row_mask:0xf bank_mask:0xf bound_ctrl:1
	v_mov_b32_dpp v120, v110 row_shl:1 row_mask:0xf bank_mask:0xf bound_ctrl:1
	v_mov_b32_dpp v113, v106 row_shr:1 row_mask:0xf bank_mask:0xf bound_ctrl:1
	v_mov_b32_dpp v124, v106 row_shl:1 row_mask:0xf bank_mask:0xf bound_ctrl:1
	v_mov_b32_dpp v119, v119 row_mirror row_mask:0xf bank_mask:0xf bound_ctrl:1
	v_mov_b32_dpp v123, v103 row_mirror row_mask:0xf bank_mask:0xf bound_ctrl:1
	v_mov_b32_dpp v114, v115 row_mirror row_mask:0xf bank_mask:0xf bound_ctrl:1
	v_mov_b32_dpp v126, v99 row_mirror row_mask:0xf bank_mask:0xf bound_ctrl:1
	v_mov_b32_dpp v121, v111 row_shr:1 row_mask:0xf bank_mask:0xf bound_ctrl:1
	v_mov_b32_dpp v125, v111 row_shl:1 row_mask:0xf bank_mask:0xf bound_ctrl:1
	v_mov_b32_dpp v115, v107 row_shr:1 row_mask:0xf bank_mask:0xf bound_ctrl:1
	v_mov_b32_dpp v178, v107 row_shl:1 row_mask:0xf bank_mask:0xf bound_ctrl:1
	v_cmp_lt_i32_e32 vcc, 30, v209
	s_mov_b64 s[22:23], 0
	v_cmp_ne_u32_e64 s[16:17], 31, v209
	s_and_saveexec_b64 s[18:19], vcc
	s_xor_b64 s[18:19], exec, s[18:19]
	s_and_b64 s[22:23], s[16:17], exec
	s_or_saveexec_b64 s[20:21], s[18:19]
	s_movk_i32 s18, 0xffe0
	v_cmp_ne_u32_e64 s[18:19], s18, v209
	s_xor_b64 exec, exec, s[20:21]
	s_andn2_b64 s[22:23], s[22:23], exec
	s_and_b64 s[44:45], s[18:19], exec
	s_or_b64 s[22:23], s[22:23], s[44:45]
	s_or_b64 exec, exec, s[20:21]
	v_add_u32_e32 v215, 32, v209
	v_cndmask_b32_e64 v216, v216, v217, s[4:5]
	v_cndmask_b32_e64 v218, v222, v218, s[6:7]
	v_add_u32_e32 v238, s42, v215
	s_and_saveexec_b64 s[20:21], s[22:23]
	s_cbranch_execz .LBB0_1719
	v_cndmask_b32_e64 v184, v225, v227, s[6:7]
	v_cndmask_b32_e64 v227, v229, v232, s[4:5]
	v_cndmask_b32_e64 v226, v223, v226, s[4:5]
	v_pk_mul_f32 v[226:227], v[216:217], v[226:227] op_sel_hi:[0,1]
	v_cndmask_b32_e64 v185, v231, v234, s[6:7]
	v_pk_mul_f32 v[224:225], v[108:109], v[200:201] op_sel_hi:[1,0]
	s_waitcnt vmcnt(4)
	v_pk_fma_f32 v[226:227], v[144:145], v[226:227], v[156:157]
	v_pk_mul_f32 v[184:185], v[218:219], v[184:185] op_sel_hi:[0,1]
	v_pk_fma_f32 v[224:225], v[224:225], v[148:149], v[226:227]
	v_cndmask_b32_e64 v181, v180, v181, s[4:5]
	v_pk_fma_f32 v[184:185], v[152:153], v[184:185], v[224:225]
	v_cndmask_b32_e64 v180, v127, v179, s[4:5]
	v_mul_f32_e32 v217, 0xbfb8aa3b, v184
	v_exp_f32_e32 v217, v217
	v_mul_f32_e32 v179, 0xbfb8aa3b, v185
	v_exp_f32_e32 v179, v179
	v_cndmask_b32_e64 v119, v119, v121, s[4:5]
	v_add_f32_e32 v127, 1.0, v217
	v_rcp_f32_e32 v226, v127
	v_add_f32_e32 v127, 1.0, v179
	v_rcp_f32_e32 v227, v127
	v_cndmask_b32_e64 v127, v126, v178, s[6:7]
	v_cndmask_b32_e64 v126, v122, v124, s[6:7]
	v_cndmask_b32_e64 v122, v118, v120, s[6:7]
	v_cndmask_b32_e64 v118, v116, v117, s[4:5]
	v_pk_mul_f32 v[118:119], v[216:217], v[118:119] op_sel_hi:[0,1]
	v_cndmask_b32_e64 v123, v123, v125, s[6:7]
	v_pk_mul_f32 v[124:125], v[110:111], v[200:201] op_sel_hi:[1,0]
	v_pk_fma_f32 v[118:119], v[146:147], v[118:119], v[158:159]
	v_pk_mul_f32 v[116:117], v[218:219], v[122:123] op_sel_hi:[0,1]
	v_pk_fma_f32 v[118:119], v[124:125], v[150:151], v[118:119]
	v_cndmask_b32_e64 v115, v114, v115, s[4:5]
	v_pk_fma_f32 v[116:117], v[154:155], v[116:117], v[118:119]
	v_cndmask_b32_e64 v114, v112, v113, s[4:5]
	v_mul_f32_e32 v118, 0xbfb8aa3b, v116
	v_mul_f32_e32 v113, 0xbfb8aa3b, v117
	v_exp_f32_e32 v120, v118
	v_exp_f32_e32 v113, v113
	v_pk_mul_f32 v[114:115], v[216:217], v[114:115] op_sel_hi:[0,1]
	v_pk_mul_f32 v[118:119], v[106:107], v[200:201] op_sel_hi:[1,0]
	v_add_f32_e32 v112, 1.0, v120
	v_add_f32_e32 v113, 1.0, v113
	v_rcp_f32_e32 v112, v112
	v_rcp_f32_e32 v113, v113
	s_waitcnt vmcnt(0)
	v_pk_fma_f32 v[114:115], v[130:131], v[114:115], v[142:143]
	v_pk_mul_f32 v[180:181], v[216:217], v[180:181] op_sel_hi:[0,1]
	v_pk_mul_f32 v[120:121], v[218:219], v[126:127] op_sel_hi:[0,1]
	v_pk_fma_f32 v[114:115], v[118:119], v[134:135], v[114:115]
	v_cndmask_b32_e64 v183, v239, v240, s[6:7]
	v_cndmask_b32_e64 v182, v230, v233, s[6:7]
	v_pk_mul_f32 v[224:225], v[104:105], v[200:201] op_sel_hi:[1,0]
	v_pk_fma_f32 v[180:181], v[128:129], v[180:181], v[140:141]
	v_pk_fma_f32 v[114:115], v[138:139], v[120:121], v[114:115]
	v_pk_mul_f32 v[112:113], v[116:117], v[112:113]
	v_pk_mul_f32 v[182:183], v[218:219], v[182:183] op_sel_hi:[0,1]
	v_pk_fma_f32 v[180:181], v[224:225], v[132:133], v[180:181]
	v_pk_mul_f32 v[112:113], v[114:115], v[112:113]
	v_pk_fma_f32 v[180:181], v[136:137], v[182:183], v[180:181]
	v_pk_mul_f32 v[182:183], v[184:185], v[226:227]
	v_cvt_pk_bf16_f32 v115, v112, v113
	v_mov_b64_e32 v[112:113], s[30:31]
	v_pk_mul_f32 v[180:181], v[180:181], v[182:183]
	v_mad_i64_i32 v[112:113], s[22:23], v238, s1, v[112:113]
	v_mov_b32_e32 v224, 0x1800
	v_cvt_pk_bf16_f32 v114, v180, v181
	v_lshl_add_u64 v[112:113], v[170:171], 1, v[112:113]
	v_mov_b32_e32 v252, v114
	v_mov_b32_e32 v253, v115
.LBB0_1719:
	s_or_b64 exec, exec, s[20:21]
	v_mov_b32_dpp v124, v108 row_mirror row_mask:0xf bank_mask:0xf bound_ctrl:1
	v_mov_b32_dpp v125, v100 row_mirror row_mask:0xf bank_mask:0xf bound_ctrl:1
	v_mov_b32_dpp v119, v104 row_mirror row_mask:0xf bank_mask:0xf bound_ctrl:1
	v_mov_b32_dpp v179, v96 row_mirror row_mask:0xf bank_mask:0xf bound_ctrl:1
	v_mov_b32_dpp v126, v100 row_shr:1 row_mask:0xf bank_mask:0xf bound_ctrl:1
	v_mov_b32_dpp v127, v100 row_shl:1 row_mask:0xf bank_mask:0xf bound_ctrl:1
	v_mov_b32_dpp v121, v96 row_shr:1 row_mask:0xf bank_mask:0xf bound_ctrl:1
	v_mov_b32_dpp v223, v96 row_shl:1 row_mask:0xf bank_mask:0xf bound_ctrl:1
	v_mov_b32_dpp v178, v109 row_mirror row_mask:0xf bank_mask:0xf bound_ctrl:1
	v_mov_b32_dpp v180, v101 row_mirror row_mask:0xf bank_mask:0xf bound_ctrl:1
	v_mov_b32_dpp v122, v105 row_mirror row_mask:0xf bank_mask:0xf bound_ctrl:1
	v_mov_b32_dpp v226, v97 row_mirror row_mask:0xf bank_mask:0xf bound_ctrl:1
	v_mov_b32_dpp v181, v101 row_shr:1 row_mask:0xf bank_mask:0xf bound_ctrl:1
	v_mov_b32_dpp v225, v101 row_shl:1 row_mask:0xf bank_mask:0xf bound_ctrl:1
	v_mov_b32_dpp v123, v97 row_shr:1 row_mask:0xf bank_mask:0xf bound_ctrl:1
	v_mov_b32_dpp v227, v97 row_shl:1 row_mask:0xf bank_mask:0xf bound_ctrl:1
	v_mov_b32_dpp v108, v110 row_mirror row_mask:0xf bank_mask:0xf bound_ctrl:1
	v_mov_b32_dpp v110, v102 row_mirror row_mask:0xf bank_mask:0xf bound_ctrl:1
	v_mov_b32_dpp v104, v106 row_mirror row_mask:0xf bank_mask:0xf bound_ctrl:1
	v_mov_b32_dpp v114, v98 row_mirror row_mask:0xf bank_mask:0xf bound_ctrl:1
	v_mov_b32_dpp v109, v102 row_shr:1 row_mask:0xf bank_mask:0xf bound_ctrl:1
	v_mov_b32_dpp v112, v102 row_shl:1 row_mask:0xf bank_mask:0xf bound_ctrl:1
	v_mov_b32_dpp v105, v98 row_shr:1 row_mask:0xf bank_mask:0xf bound_ctrl:1
	v_mov_b32_dpp v116, v98 row_shl:1 row_mask:0xf bank_mask:0xf bound_ctrl:1
	v_mov_b32_dpp v111, v111 row_mirror row_mask:0xf bank_mask:0xf bound_ctrl:1
	v_mov_b32_dpp v115, v103 row_mirror row_mask:0xf bank_mask:0xf bound_ctrl:1
	v_mov_b32_dpp v106, v107 row_mirror row_mask:0xf bank_mask:0xf bound_ctrl:1
	v_mov_b32_dpp v118, v99 row_mirror row_mask:0xf bank_mask:0xf bound_ctrl:1
	v_mov_b32_dpp v113, v103 row_shr:1 row_mask:0xf bank_mask:0xf bound_ctrl:1
	v_mov_b32_dpp v117, v103 row_shl:1 row_mask:0xf bank_mask:0xf bound_ctrl:1
	v_mov_b32_dpp v107, v99 row_shr:1 row_mask:0xf bank_mask:0xf bound_ctrl:1
	v_mov_b32_dpp v120, v99 row_shl:1 row_mask:0xf bank_mask:0xf bound_ctrl:1
	v_cmp_lt_i32_e32 vcc, 14, v209
	s_mov_b64 s[48:49], 0
	v_cmp_ne_u32_e64 s[20:21], 15, v209
	s_and_saveexec_b64 s[22:23], vcc
	s_xor_b64 s[22:23], exec, s[22:23]
	s_and_b64 s[48:49], s[20:21], exec
	s_or_saveexec_b64 s[44:45], s[22:23]
	s_movk_i32 s22, 0xffd0
	v_cmp_ne_u32_e64 s[22:23], s22, v209
	s_xor_b64 exec, exec, s[44:45]
	s_andn2_b64 s[48:49], s[48:49], exec
	s_and_b64 vcc, s[22:23], exec
	s_or_b64 s[48:49], s[48:49], vcc
	s_or_b64 exec, exec, s[44:45]
	v_add_u32_e32 v217, 48, v209
	v_cndmask_b32_e64 v220, v219, v220, s[4:5]
	v_cndmask_b32_e64 v222, v222, v236, s[6:7]
	v_add_u32_e32 v219, s42, v217
	s_and_saveexec_b64 s[44:45], s[48:49]
	s_cbranch_execz .LBB0_1725
	v_cndmask_b32_e64 v184, v125, v127, s[6:7]
	v_cndmask_b32_e64 v125, v178, v181, s[4:5]
	v_cndmask_b32_e64 v124, v124, v126, s[4:5]
	v_pk_mul_f32 v[124:125], v[220:221], v[124:125] op_sel_hi:[0,1]
	v_cndmask_b32_e64 v185, v180, v225, s[6:7]
	v_pk_mul_f32 v[100:101], v[100:101], v[186:187] op_sel_hi:[1,0]
	s_waitcnt vmcnt(4)
	v_pk_fma_f32 v[124:125], v[144:145], v[124:125], v[156:157]
	v_pk_mul_f32 v[126:127], v[222:223], v[184:185] op_sel_hi:[0,1]
	v_pk_fma_f32 v[100:101], v[100:101], v[148:149], v[124:125]
	v_cndmask_b32_e64 v123, v122, v123, s[4:5]
	v_pk_fma_f32 v[100:101], v[152:153], v[126:127], v[100:101]
	v_cndmask_b32_e64 v122, v119, v121, s[4:5]
	v_mul_f32_e32 v124, 0xbfb8aa3b, v100
	v_exp_f32_e32 v124, v124
	v_mul_f32_e32 v121, 0xbfb8aa3b, v101
	v_exp_f32_e32 v121, v121
	v_pk_mul_f32 v[122:123], v[220:221], v[122:123] op_sel_hi:[0,1]
	v_add_f32_e32 v119, 1.0, v124
	v_rcp_f32_e32 v124, v119
	v_add_f32_e32 v119, 1.0, v121
	v_rcp_f32_e32 v125, v119
	v_cndmask_b32_e64 v183, v226, v227, s[6:7]
	v_cndmask_b32_e64 v182, v179, v223, s[6:7]
	v_pk_mul_f32 v[96:97], v[96:97], v[186:187] op_sel_hi:[1,0]
	s_waitcnt vmcnt(0)
	v_pk_fma_f32 v[122:123], v[128:129], v[122:123], v[140:141]
	v_pk_mul_f32 v[126:127], v[222:223], v[182:183] op_sel_hi:[0,1]
	v_pk_fma_f32 v[96:97], v[96:97], v[132:133], v[122:123]
	v_pk_mul_f32 v[100:101], v[100:101], v[124:125]
	v_pk_fma_f32 v[96:97], v[136:137], v[126:127], v[96:97]
	v_cndmask_b32_e64 v111, v111, v113, s[4:5]
	v_pk_mul_f32 v[96:97], v[96:97], v[100:101]
	v_cndmask_b32_e64 v100, v114, v116, s[6:7]
	v_cndmask_b32_e64 v114, v110, v112, s[6:7]
	v_cndmask_b32_e64 v110, v108, v109, s[4:5]
	v_pk_mul_f32 v[110:111], v[220:221], v[110:111] op_sel_hi:[0,1]
	v_cndmask_b32_e64 v115, v115, v117, s[6:7]
	v_pk_mul_f32 v[102:103], v[102:103], v[186:187] op_sel_hi:[1,0]
	v_pk_fma_f32 v[110:111], v[146:147], v[110:111], v[158:159]
	v_pk_mul_f32 v[108:109], v[222:223], v[114:115] op_sel_hi:[0,1]
	v_pk_fma_f32 v[102:103], v[102:103], v[150:151], v[110:111]
	v_cndmask_b32_e64 v107, v106, v107, s[4:5]
	v_pk_fma_f32 v[102:103], v[154:155], v[108:109], v[102:103]
	v_cndmask_b32_e64 v106, v104, v105, s[4:5]
	v_mul_f32_e32 v108, 0xbfb8aa3b, v102
	v_mul_f32_e32 v105, 0xbfb8aa3b, v103
	v_exp_f32_e32 v108, v108
	v_exp_f32_e32 v105, v105
	v_pk_mul_f32 v[106:107], v[220:221], v[106:107] op_sel_hi:[0,1]
	v_cndmask_b32_e64 v101, v118, v120, s[6:7]
	v_add_f32_e32 v104, 1.0, v108
	v_add_f32_e32 v105, 1.0, v105
	v_rcp_f32_e32 v104, v104
	v_rcp_f32_e32 v105, v105
	v_pk_mul_f32 v[98:99], v[98:99], v[186:187] op_sel_hi:[1,0]
	v_pk_fma_f32 v[106:107], v[130:131], v[106:107], v[142:143]
	v_pk_mul_f32 v[100:101], v[222:223], v[100:101] op_sel_hi:[0,1]
	v_pk_fma_f32 v[98:99], v[98:99], v[134:135], v[106:107]
	v_cvt_pk_bf16_f32 v96, v96, v97
	v_pk_fma_f32 v[98:99], v[138:139], v[100:101], v[98:99]
	v_pk_mul_f32 v[100:101], v[102:103], v[104:105]
	s_nop 0
	v_pk_mul_f32 v[98:99], v[98:99], v[100:101]
	s_nop 0
	v_cvt_pk_bf16_f32 v97, v98, v99
	v_mov_b64_e32 v[98:99], s[30:31]
	v_mad_i64_i32 v[98:99], s[48:49], v219, s1, v[98:99]
	v_lshl_add_u64 v[98:99], v[170:171], 1, v[98:99]
	v_mov_b32_e32 v246, v96
	v_mov_b32_e32 v247, v97

.LBB0_1728:
	v_cndmask_b32_e64 v184, v178, v180, s[6:7]
	v_cndmask_b32_e64 v181, v181, v227, s[4:5]
	v_cndmask_b32_e64 v180, v225, v179, s[4:5]
	v_pk_mul_f32 v[180:181], v[208:209], v[180:181] op_sel_hi:[0,1]
	v_cndmask_b32_e64 v182, v223, v229, s[6:7]
	v_cndmask_b32_e64 v185, v226, v230, s[6:7]
	v_pk_mul_f32 v[228:229], v[92:93], v[206:207] op_sel_hi:[1,0]
	s_waitcnt vmcnt(4)
	v_pk_fma_f32 v[180:181], v[112:113], v[180:181], v[124:125]
	v_pk_mul_f32 v[178:179], v[210:211], v[184:185] op_sel_hi:[0,1]
	v_pk_fma_f32 v[180:181], v[228:229], v[116:117], v[180:181]
	v_cndmask_b32_e64 v159, v158, v159, s[4:5]
	v_pk_fma_f32 v[178:179], v[120:121], v[178:179], v[180:181]
	v_cndmask_b32_e64 v158, v155, v157, s[4:5]
	v_mul_f32_e32 v180, 0xbfb8aa3b, v178
	v_exp_f32_e32 v184, v180
	v_mul_f32_e32 v157, 0xbfb8aa3b, v179
	v_exp_f32_e32 v157, v157
	v_cndmask_b32_e64 v147, v147, v149, s[4:5]
	v_add_f32_e32 v155, 1.0, v184
	v_rcp_f32_e32 v184, v155
	v_add_f32_e32 v155, 1.0, v157
	v_rcp_f32_e32 v185, v155
	v_cndmask_b32_e64 v155, v154, v156, s[6:7]
	v_cndmask_b32_e64 v154, v150, v152, s[6:7]
	v_cndmask_b32_e64 v150, v146, v148, s[6:7]
	v_cndmask_b32_e64 v146, v144, v145, s[4:5]
	v_pk_mul_f32 v[146:147], v[208:209], v[146:147] op_sel_hi:[0,1]
	v_cndmask_b32_e64 v151, v151, v153, s[6:7]
	v_pk_mul_f32 v[152:153], v[94:95], v[206:207] op_sel_hi:[1,0]
	v_pk_fma_f32 v[146:147], v[114:115], v[146:147], v[126:127]
	v_pk_mul_f32 v[144:145], v[210:211], v[150:151] op_sel_hi:[0,1]
	v_pk_fma_f32 v[146:147], v[152:153], v[118:119], v[146:147]
	v_cndmask_b32_e64 v143, v142, v143, s[4:5]
	v_pk_fma_f32 v[144:145], v[122:123], v[144:145], v[146:147]
	v_cndmask_b32_e64 v142, v140, v141, s[4:5]
	v_mul_f32_e32 v146, 0xbfb8aa3b, v144
	v_mul_f32_e32 v141, 0xbfb8aa3b, v145
	v_exp_f32_e32 v148, v146
	v_exp_f32_e32 v141, v141
	v_pk_mul_f32 v[142:143], v[208:209], v[142:143] op_sel_hi:[0,1]
	v_pk_mul_f32 v[146:147], v[90:91], v[206:207] op_sel_hi:[1,0]
	v_add_f32_e32 v140, 1.0, v148
	v_add_f32_e32 v141, 1.0, v141
	v_rcp_f32_e32 v140, v140
	v_rcp_f32_e32 v141, v141
	s_waitcnt vmcnt(0)
	v_pk_fma_f32 v[142:143], v[98:99], v[142:143], v[110:111]
	v_pk_mul_f32 v[158:159], v[208:209], v[158:159] op_sel_hi:[0,1]
	v_pk_mul_f32 v[148:149], v[210:211], v[154:155] op_sel_hi:[0,1]
	v_pk_fma_f32 v[142:143], v[146:147], v[102:103], v[142:143]
	v_cndmask_b32_e64 v183, v231, v232, s[6:7]
	v_pk_mul_f32 v[180:181], v[88:89], v[206:207] op_sel_hi:[1,0]
	v_pk_fma_f32 v[158:159], v[96:97], v[158:159], v[108:109]
	v_pk_fma_f32 v[142:143], v[106:107], v[148:149], v[142:143]
	v_pk_mul_f32 v[140:141], v[144:145], v[140:141]
	v_pk_mul_f32 v[182:183], v[210:211], v[182:183] op_sel_hi:[0,1]
	v_pk_fma_f32 v[158:159], v[180:181], v[100:101], v[158:159]
	v_pk_mul_f32 v[140:141], v[142:143], v[140:141]
	v_pk_fma_f32 v[158:159], v[104:105], v[182:183], v[158:159]
	v_pk_mul_f32 v[178:179], v[178:179], v[184:185]
	v_cvt_pk_bf16_f32 v143, v140, v141
	v_mov_b64_e32 v[140:141], s[30:31]
	v_pk_mul_f32 v[158:159], v[158:159], v[178:179]
	v_mad_i64_i32 v[140:141], s[48:49], v204, s1, v[140:141]
	v_cvt_pk_bf16_f32 v142, v158, v159
	v_lshl_add_u64 v[140:141], v[170:171], 1, v[140:141]
	v_mov_b32_e32 v178, v248
	v_mov_b32_e32 v179, v249
	v_mov_b32_e32 v180, v142
	v_mov_b32_e32 v181, v143
	global_store_dwordx4 v[140:141], v[178:181], off

.LBB0_1732:
	v_cndmask_b32_e64 v181, v180, v181, s[6:7]
	v_cndmask_b32_e64 v180, v157, v178, s[6:7]
	v_cndmask_b32_e64 v178, v153, v155, s[6:7]
	v_cndmask_b32_e64 v153, v156, v159, s[4:5]
	v_cndmask_b32_e64 v152, v152, v154, s[4:5]
	v_pk_mul_f32 v[152:153], v[212:213], v[152:153] op_sel_hi:[0,1]
	v_cndmask_b32_e64 v179, v158, v179, s[6:7]
	v_pk_mul_f32 v[182:183], v[84:85], v[202:203] op_sel_hi:[1,0]
	s_waitcnt vmcnt(4)
	v_pk_fma_f32 v[152:153], v[112:113], v[152:153], v[124:125]
	v_pk_mul_f32 v[154:155], v[214:215], v[178:179] op_sel_hi:[0,1]
	v_pk_fma_f32 v[152:153], v[182:183], v[116:117], v[152:153]
	v_cndmask_b32_e64 v151, v150, v151, s[4:5]
	v_pk_fma_f32 v[152:153], v[120:121], v[154:155], v[152:153]
	v_cndmask_b32_e64 v150, v147, v149, s[4:5]
	v_mul_f32_e32 v154, 0xbfb8aa3b, v152
	v_exp_f32_e32 v156, v154
	v_mul_f32_e32 v149, 0xbfb8aa3b, v153
	v_exp_f32_e32 v149, v149
	v_cndmask_b32_e64 v95, v95, v141, s[4:5]
	v_add_f32_e32 v147, 1.0, v156
	v_rcp_f32_e32 v156, v147
	v_add_f32_e32 v147, 1.0, v149
	v_rcp_f32_e32 v157, v147
	v_cndmask_b32_e64 v147, v146, v148, s[6:7]
	v_cndmask_b32_e64 v146, v142, v144, s[6:7]
	v_cndmask_b32_e64 v142, v94, v140, s[6:7]
	v_cndmask_b32_e64 v94, v92, v93, s[4:5]
	v_pk_mul_f32 v[94:95], v[212:213], v[94:95] op_sel_hi:[0,1]
	v_cndmask_b32_e64 v143, v143, v145, s[6:7]
	v_pk_mul_f32 v[144:145], v[86:87], v[202:203] op_sel_hi:[1,0]
	v_pk_fma_f32 v[94:95], v[114:115], v[94:95], v[126:127]
	v_pk_mul_f32 v[92:93], v[214:215], v[142:143] op_sel_hi:[0,1]
	v_pk_fma_f32 v[94:95], v[144:145], v[118:119], v[94:95]
	v_cndmask_b32_e64 v91, v90, v91, s[4:5]
	v_pk_fma_f32 v[92:93], v[122:123], v[92:93], v[94:95]
	v_cndmask_b32_e64 v90, v88, v89, s[4:5]
	v_mul_f32_e32 v94, 0xbfb8aa3b, v92
	v_mul_f32_e32 v89, 0xbfb8aa3b, v93
	v_exp_f32_e32 v140, v94
	v_exp_f32_e32 v89, v89
	v_pk_mul_f32 v[90:91], v[212:213], v[90:91] op_sel_hi:[0,1]
	v_pk_mul_f32 v[94:95], v[82:83], v[202:203] op_sel_hi:[1,0]
	v_add_f32_e32 v88, 1.0, v140
	v_add_f32_e32 v89, 1.0, v89
	v_rcp_f32_e32 v88, v88
	v_rcp_f32_e32 v89, v89
	s_waitcnt vmcnt(0)
	v_pk_fma_f32 v[90:91], v[98:99], v[90:91], v[110:111]
	v_pk_mul_f32 v[150:151], v[212:213], v[150:151] op_sel_hi:[0,1]
	v_pk_mul_f32 v[140:141], v[214:215], v[146:147] op_sel_hi:[0,1]
	v_pk_fma_f32 v[90:91], v[94:95], v[102:103], v[90:91]
	v_pk_mul_f32 v[154:155], v[80:81], v[202:203] op_sel_hi:[1,0]
	v_pk_fma_f32 v[150:151], v[96:97], v[150:151], v[108:109]
	v_pk_fma_f32 v[90:91], v[106:107], v[140:141], v[90:91]
	v_pk_mul_f32 v[88:89], v[92:93], v[88:89]
	v_pk_mul_f32 v[158:159], v[214:215], v[180:181] op_sel_hi:[0,1]
	v_pk_fma_f32 v[150:151], v[154:155], v[100:101], v[150:151]
	v_pk_mul_f32 v[88:89], v[90:91], v[88:89]
	v_pk_fma_f32 v[150:151], v[104:105], v[158:159], v[150:151]
	v_pk_mul_f32 v[152:153], v[152:153], v[156:157]
	v_cvt_pk_bf16_f32 v91, v88, v89
	v_mov_b64_e32 v[88:89], s[30:31]
	v_pk_mul_f32 v[150:151], v[150:151], v[152:153]
	v_mad_i64_i32 v[88:89], s[48:49], v237, s1, v[88:89]
	v_cvt_pk_bf16_f32 v90, v150, v151
	v_lshl_add_u64 v[88:89], v[170:171], 1, v[88:89]
	v_mov_b32_e32 v178, v250
	v_mov_b32_e32 v179, v251
	v_mov_b32_e32 v180, v90
	v_mov_b32_e32 v181, v91
	global_store_dwordx4 v[88:89], v[178:181], off

.LBB0_1736:
	v_cndmask_b32_e64 v155, v154, v155, s[6:7]
	v_cndmask_b32_e64 v154, v149, v152, s[6:7]
	v_cndmask_b32_e64 v152, v145, v147, s[6:7]
	v_cndmask_b32_e64 v145, v148, v151, s[4:5]
	v_cndmask_b32_e64 v144, v144, v146, s[4:5]
	v_pk_mul_f32 v[144:145], v[216:217], v[144:145] op_sel_hi:[0,1]
	v_cndmask_b32_e64 v153, v150, v153, s[6:7]
	v_pk_mul_f32 v[156:157], v[76:77], v[200:201] op_sel_hi:[1,0]
	s_waitcnt vmcnt(4)
	v_pk_fma_f32 v[144:145], v[112:113], v[144:145], v[124:125]
	v_pk_mul_f32 v[146:147], v[218:219], v[152:153] op_sel_hi:[0,1]
	v_pk_fma_f32 v[144:145], v[156:157], v[116:117], v[144:145]
	v_cndmask_b32_e64 v143, v142, v143, s[4:5]
	v_pk_fma_f32 v[144:145], v[120:121], v[146:147], v[144:145]
	v_cndmask_b32_e64 v142, v95, v141, s[4:5]
	v_mul_f32_e32 v146, 0xbfb8aa3b, v144
	v_exp_f32_e32 v148, v146
	v_mul_f32_e32 v141, 0xbfb8aa3b, v145
	v_exp_f32_e32 v141, v141
	v_cndmask_b32_e64 v87, v87, v89, s[4:5]
	v_add_f32_e32 v95, 1.0, v148
	v_rcp_f32_e32 v148, v95
	v_add_f32_e32 v95, 1.0, v141
	v_rcp_f32_e32 v149, v95
	v_cndmask_b32_e64 v95, v94, v140, s[6:7]
	v_cndmask_b32_e64 v94, v90, v92, s[6:7]
	v_cndmask_b32_e64 v90, v86, v88, s[6:7]
	v_cndmask_b32_e64 v86, v84, v85, s[4:5]
	v_pk_mul_f32 v[86:87], v[216:217], v[86:87] op_sel_hi:[0,1]
	v_cndmask_b32_e64 v91, v91, v93, s[6:7]
	v_pk_mul_f32 v[92:93], v[78:79], v[200:201] op_sel_hi:[1,0]
	v_pk_fma_f32 v[86:87], v[114:115], v[86:87], v[126:127]
	v_pk_mul_f32 v[84:85], v[218:219], v[90:91] op_sel_hi:[0,1]
	v_pk_fma_f32 v[86:87], v[92:93], v[118:119], v[86:87]
	v_cndmask_b32_e64 v83, v82, v83, s[4:5]
	v_pk_fma_f32 v[84:85], v[122:123], v[84:85], v[86:87]
	v_cndmask_b32_e64 v82, v80, v81, s[4:5]
	v_mul_f32_e32 v86, 0xbfb8aa3b, v84
	v_mul_f32_e32 v81, 0xbfb8aa3b, v85
	v_exp_f32_e32 v88, v86
	v_exp_f32_e32 v81, v81
	v_pk_mul_f32 v[82:83], v[216:217], v[82:83] op_sel_hi:[0,1]
	v_pk_mul_f32 v[86:87], v[74:75], v[200:201] op_sel_hi:[1,0]
	v_add_f32_e32 v80, 1.0, v88
	v_add_f32_e32 v81, 1.0, v81
	v_rcp_f32_e32 v80, v80
	v_rcp_f32_e32 v81, v81
	s_waitcnt vmcnt(0)
	v_pk_fma_f32 v[82:83], v[98:99], v[82:83], v[110:111]
	v_pk_mul_f32 v[142:143], v[216:217], v[142:143] op_sel_hi:[0,1]
	v_pk_mul_f32 v[88:89], v[218:219], v[94:95] op_sel_hi:[0,1]
	v_pk_fma_f32 v[82:83], v[86:87], v[102:103], v[82:83]
	v_pk_mul_f32 v[146:147], v[72:73], v[200:201] op_sel_hi:[1,0]
	v_pk_fma_f32 v[142:143], v[96:97], v[142:143], v[108:109]
	v_pk_fma_f32 v[82:83], v[106:107], v[88:89], v[82:83]
	v_pk_mul_f32 v[80:81], v[84:85], v[80:81]
	v_pk_mul_f32 v[150:151], v[218:219], v[154:155] op_sel_hi:[0,1]
	v_pk_fma_f32 v[142:143], v[146:147], v[100:101], v[142:143]
	v_pk_mul_f32 v[80:81], v[82:83], v[80:81]
	v_pk_fma_f32 v[142:143], v[104:105], v[150:151], v[142:143]
	v_pk_mul_f32 v[144:145], v[144:145], v[148:149]
	v_cvt_pk_bf16_f32 v83, v80, v81
	v_mov_b64_e32 v[80:81], s[30:31]
	v_pk_mul_f32 v[142:143], v[142:143], v[144:145]
	v_mad_i64_i32 v[80:81], s[48:49], v238, s1, v[80:81]
	v_cvt_pk_bf16_f32 v82, v142, v143
	v_lshl_add_u64 v[80:81], v[170:171], 1, v[80:81]
	v_mov_b32_e32 v178, v252
	v_mov_b32_e32 v179, v253
	v_mov_b32_e32 v180, v82
	v_mov_b32_e32 v181, v83
	global_store_dwordx4 v[80:81], v[178:181], off

.LBB0_1740:
	v_cndmask_b32_e64 v147, v146, v147, s[6:7]
	v_cndmask_b32_e64 v146, v141, v144, s[6:7]
	v_cndmask_b32_e64 v144, v93, v95, s[6:7]
	v_cndmask_b32_e64 v93, v140, v143, s[4:5]
	v_cndmask_b32_e64 v92, v92, v94, s[4:5]
	v_pk_mul_f32 v[92:93], v[220:221], v[92:93] op_sel_hi:[0,1]
	v_cndmask_b32_e64 v145, v142, v145, s[6:7]
	v_pk_mul_f32 v[68:69], v[68:69], v[186:187] op_sel_hi:[1,0]
	s_waitcnt vmcnt(4)
	v_pk_fma_f32 v[92:93], v[112:113], v[92:93], v[124:125]
	v_pk_mul_f32 v[94:95], v[222:223], v[144:145] op_sel_hi:[0,1]
	v_pk_fma_f32 v[68:69], v[68:69], v[116:117], v[92:93]
	v_cndmask_b32_e64 v91, v90, v91, s[4:5]
	v_pk_fma_f32 v[68:69], v[120:121], v[94:95], v[68:69]
	v_cndmask_b32_e64 v90, v87, v89, s[4:5]
	v_mul_f32_e32 v92, 0xbfb8aa3b, v68
	v_exp_f32_e32 v92, v92
	v_mul_f32_e32 v89, 0xbfb8aa3b, v69
	v_exp_f32_e32 v89, v89
	v_pk_mul_f32 v[90:91], v[220:221], v[90:91] op_sel_hi:[0,1]
	v_add_f32_e32 v87, 1.0, v92
	v_rcp_f32_e32 v92, v87
	v_add_f32_e32 v87, 1.0, v89
	v_rcp_f32_e32 v93, v87
	v_pk_mul_f32 v[64:65], v[64:65], v[186:187] op_sel_hi:[1,0]
	s_waitcnt vmcnt(0)
	v_pk_fma_f32 v[90:91], v[96:97], v[90:91], v[108:109]
	v_pk_mul_f32 v[94:95], v[222:223], v[146:147] op_sel_hi:[0,1]
	v_pk_fma_f32 v[64:65], v[64:65], v[100:101], v[90:91]
	v_pk_mul_f32 v[68:69], v[68:69], v[92:93]
	v_pk_fma_f32 v[64:65], v[104:105], v[94:95], v[64:65]
	v_cndmask_b32_e64 v79, v79, v81, s[4:5]
	v_pk_mul_f32 v[64:65], v[64:65], v[68:69]
	v_cndmask_b32_e64 v68, v82, v84, s[6:7]
	v_cndmask_b32_e64 v82, v78, v80, s[6:7]
	v_cndmask_b32_e64 v78, v76, v77, s[4:5]
	v_pk_mul_f32 v[78:79], v[220:221], v[78:79] op_sel_hi:[0,1]
	v_cndmask_b32_e64 v83, v83, v85, s[6:7]
	v_pk_mul_f32 v[70:71], v[70:71], v[186:187] op_sel_hi:[1,0]
	v_pk_fma_f32 v[78:79], v[114:115], v[78:79], v[126:127]
	v_pk_mul_f32 v[76:77], v[222:223], v[82:83] op_sel_hi:[0,1]
	v_pk_fma_f32 v[70:71], v[70:71], v[118:119], v[78:79]
	v_cndmask_b32_e64 v75, v74, v75, s[4:5]
	v_pk_fma_f32 v[70:71], v[122:123], v[76:77], v[70:71]
	v_cndmask_b32_e64 v74, v72, v73, s[4:5]
	v_mul_f32_e32 v76, 0xbfb8aa3b, v70
	v_mul_f32_e32 v73, 0xbfb8aa3b, v71
	v_exp_f32_e32 v76, v76
	v_exp_f32_e32 v73, v73
	v_pk_mul_f32 v[74:75], v[220:221], v[74:75] op_sel_hi:[0,1]
	v_cndmask_b32_e64 v69, v86, v88, s[6:7]
	v_add_f32_e32 v72, 1.0, v76
	v_add_f32_e32 v73, 1.0, v73
	v_rcp_f32_e32 v72, v72
	v_rcp_f32_e32 v73, v73
	v_pk_mul_f32 v[66:67], v[66:67], v[186:187] op_sel_hi:[1,0]
	v_pk_fma_f32 v[74:75], v[98:99], v[74:75], v[110:111]
	v_pk_mul_f32 v[68:69], v[222:223], v[68:69] op_sel_hi:[0,1]
	v_pk_fma_f32 v[66:67], v[66:67], v[102:103], v[74:75]
	v_cvt_pk_bf16_f32 v64, v64, v65
	v_pk_fma_f32 v[66:67], v[106:107], v[68:69], v[66:67]
	v_pk_mul_f32 v[68:69], v[70:71], v[72:73]
	s_nop 0
	v_pk_mul_f32 v[66:67], v[66:67], v[68:69]
	s_nop 0
	v_cvt_pk_bf16_f32 v65, v66, v67
	v_mov_b64_e32 v[66:67], s[30:31]
	v_mad_i64_i32 v[66:67], s[48:49], v219, s1, v[66:67]
	v_lshl_add_u64 v[66:67], v[170:171], 1, v[66:67]
	v_mov_b32_e32 v178, v246
	v_mov_b32_e32 v179, v247
	v_mov_b32_e32 v180, v64
	v_mov_b32_e32 v181, v65
	global_store_dwordx4 v[66:67], v[178:181], off

.LBB0_1745:
	s_or_b64 exec, exec, s[24:25]
	global_load_dwordx4 v[80:83], v[172:173], off
	global_load_dwordx4 v[84:87], v[188:189], off
	global_load_dwordx4 v[88:91], v[190:191], off
	global_load_dwordx4 v[92:95], v[174:175], off
	global_load_dwordx4 v[64:67], v[192:193], off
	global_load_dwordx4 v[68:71], v[194:195], off
	global_load_dwordx4 v[72:75], v[196:197], off
	global_load_dwordx4 v[76:79], v[198:199], off
	v_mov_b32_dpp v145, v60 row_mirror row_mask:0xf bank_mask:0xf bound_ctrl:1
	v_mov_b32_dpp v146, v52 row_mirror row_mask:0xf bank_mask:0xf bound_ctrl:1
	v_mov_b32_dpp v140, v56 row_mirror row_mask:0xf bank_mask:0xf bound_ctrl:1
	v_mov_b32_dpp v150, v48 row_mirror row_mask:0xf bank_mask:0xf bound_ctrl:1
	v_mov_b32_dpp v147, v60 row_shr:1 row_mask:0xf bank_mask:0xf bound_ctrl:1
	v_mov_b32_dpp v148, v60 row_shl:1 row_mask:0xf bank_mask:0xf bound_ctrl:1
	v_mov_b32_dpp v142, v56 row_shr:1 row_mask:0xf bank_mask:0xf bound_ctrl:1
	v_mov_b32_dpp v153, v56 row_shl:1 row_mask:0xf bank_mask:0xf bound_ctrl:1
	v_mov_b32_dpp v149, v61 row_mirror row_mask:0xf bank_mask:0xf bound_ctrl:1
	v_mov_b32_dpp v151, v53 row_mirror row_mask:0xf bank_mask:0xf bound_ctrl:1
	v_mov_b32_dpp v143, v57 row_mirror row_mask:0xf bank_mask:0xf bound_ctrl:1
	v_mov_b32_dpp v155, v49 row_mirror row_mask:0xf bank_mask:0xf bound_ctrl:1
	v_mov_b32_dpp v152, v61 row_shr:1 row_mask:0xf bank_mask:0xf bound_ctrl:1
	v_mov_b32_dpp v154, v61 row_shl:1 row_mask:0xf bank_mask:0xf bound_ctrl:1
	v_mov_b32_dpp v144, v57 row_shr:1 row_mask:0xf bank_mask:0xf bound_ctrl:1
	v_mov_b32_dpp v156, v57 row_shl:1 row_mask:0xf bank_mask:0xf bound_ctrl:1
	v_mov_b32_dpp v117, v62 row_mirror row_mask:0xf bank_mask:0xf bound_ctrl:1
	v_mov_b32_dpp v119, v54 row_mirror row_mask:0xf bank_mask:0xf bound_ctrl:1
	v_mov_b32_dpp v113, v58 row_mirror row_mask:0xf bank_mask:0xf bound_ctrl:1
	v_mov_b32_dpp v123, v50 row_mirror row_mask:0xf bank_mask:0xf bound_ctrl:1
	v_mov_b32_dpp v118, v62 row_shr:1 row_mask:0xf bank_mask:0xf bound_ctrl:1
	v_mov_b32_dpp v121, v62 row_shl:1 row_mask:0xf bank_mask:0xf bound_ctrl:1
	v_mov_b32_dpp v114, v58 row_shr:1 row_mask:0xf bank_mask:0xf bound_ctrl:1
	v_mov_b32_dpp v125, v58 row_shl:1 row_mask:0xf bank_mask:0xf bound_ctrl:1
	v_mov_b32_dpp v120, v63 row_mirror row_mask:0xf bank_mask:0xf bound_ctrl:1
	v_mov_b32_dpp v124, v55 row_mirror row_mask:0xf bank_mask:0xf bound_ctrl:1
	v_mov_b32_dpp v115, v59 row_mirror row_mask:0xf bank_mask:0xf bound_ctrl:1
	v_mov_b32_dpp v127, v51 row_mirror row_mask:0xf bank_mask:0xf bound_ctrl:1
	v_mov_b32_dpp v122, v63 row_shr:1 row_mask:0xf bank_mask:0xf bound_ctrl:1
	v_mov_b32_dpp v126, v63 row_shl:1 row_mask:0xf bank_mask:0xf bound_ctrl:1
	v_mov_b32_dpp v116, v59 row_shr:1 row_mask:0xf bank_mask:0xf bound_ctrl:1
	v_mov_b32_dpp v141, v59 row_shl:1 row_mask:0xf bank_mask:0xf bound_ctrl:1
	v_cmp_lt_i32_e32 vcc, 62, v209
	s_mov_b64 s[26:27], 0
	s_and_saveexec_b64 s[24:25], vcc
	s_xor_b64 s[24:25], exec, s[24:25]
	s_and_b64 s[26:27], s[10:11], exec
	s_andn2_saveexec_b64 s[24:25], s[24:25]
	s_andn2_b64 s[26:27], s[26:27], exec
	s_and_b64 s[44:45], s[8:9], exec
	s_or_b64 s[26:27], s[26:27], s[44:45]
	s_or_b64 exec, exec, s[24:25]
	v_cndmask_b32_e64 v106, v97, v106, s[4:5]
	v_cndmask_b32_e64 v108, v99, v108, s[6:7]
	s_and_saveexec_b64 s[24:25], s[26:27]
	s_cbranch_execz .LBB0_1751
	v_cndmask_b32_e64 v157, v155, v156, s[6:7]
	v_cndmask_b32_e64 v156, v150, v153, s[6:7]
	v_cndmask_b32_e64 v150, v146, v148, s[6:7]
	v_cndmask_b32_e64 v149, v149, v152, s[4:5]
	v_cndmask_b32_e64 v148, v145, v147, s[4:5]
	v_pk_mul_f32 v[148:149], v[106:107], v[148:149] op_sel_hi:[0,1]
	v_cndmask_b32_e64 v151, v151, v154, s[6:7]
	v_pk_mul_f32 v[154:155], v[60:61], v[104:105] op_sel_hi:[1,0]
	s_waitcnt vmcnt(4)
	v_pk_fma_f32 v[148:149], v[80:81], v[148:149], v[92:93]
	v_pk_mul_f32 v[146:147], v[108:109], v[150:151] op_sel_hi:[0,1]
	v_pk_fma_f32 v[148:149], v[154:155], v[84:85], v[148:149]
	v_cndmask_b32_e64 v143, v143, v144, s[4:5]
	v_pk_fma_f32 v[146:147], v[88:89], v[146:147], v[148:149]
	v_cndmask_b32_e64 v142, v140, v142, s[4:5]
	v_mul_f32_e32 v145, 0xbfb8aa3b, v146
	v_exp_f32_e32 v145, v145
	v_mul_f32_e32 v144, 0xbfb8aa3b, v147
	v_cndmask_b32_e64 v118, v117, v118, s[4:5]
	v_cndmask_b32_e64 v141, v127, v141, s[6:7]
	v_add_f32_e32 v140, 1.0, v145
	v_exp_f32_e32 v145, v144
	v_rcp_f32_e32 v144, v140
	v_cndmask_b32_e64 v115, v115, v116, s[4:5]
	v_cndmask_b32_e64 v114, v113, v114, s[4:5]
	v_add_f32_e32 v140, 1.0, v145
	v_rcp_f32_e32 v145, v140
	v_cndmask_b32_e64 v140, v123, v125, s[6:7]
	v_cndmask_b32_e64 v125, v124, v126, s[6:7]
	v_cndmask_b32_e64 v124, v119, v121, s[6:7]
	v_cndmask_b32_e64 v119, v120, v122, s[4:5]
	v_pk_mul_f32 v[118:119], v[106:107], v[118:119] op_sel_hi:[0,1]
	v_pk_mul_f32 v[126:127], v[62:63], v[104:105] op_sel_hi:[1,0]
	v_pk_fma_f32 v[118:119], v[82:83], v[118:119], v[94:95]
	v_pk_mul_f32 v[120:121], v[108:109], v[124:125] op_sel_hi:[0,1]
	v_pk_fma_f32 v[118:119], v[126:127], v[86:87], v[118:119]
	v_pk_mul_f32 v[114:115], v[106:107], v[114:115] op_sel_hi:[0,1]
	v_pk_fma_f32 v[118:119], v[90:91], v[120:121], v[118:119]
	v_pk_mul_f32 v[120:121], v[58:59], v[104:105] op_sel_hi:[1,0]
	v_mul_f32_e32 v117, 0xbfb8aa3b, v118
	v_exp_f32_e32 v117, v117
	v_mul_f32_e32 v116, 0xbfb8aa3b, v119
	s_waitcnt vmcnt(0)
	v_pk_fma_f32 v[114:115], v[66:67], v[114:115], v[78:79]
	v_pk_mul_f32 v[142:143], v[106:107], v[142:143] op_sel_hi:[0,1]
	v_add_f32_e32 v113, 1.0, v117
	v_exp_f32_e32 v117, v116
	v_rcp_f32_e32 v116, v113
	v_pk_mul_f32 v[122:123], v[108:109], v[140:141] op_sel_hi:[0,1]
	v_pk_fma_f32 v[114:115], v[120:121], v[70:71], v[114:115]
	v_add_f32_e32 v113, 1.0, v117
	v_rcp_f32_e32 v117, v113
	v_pk_mul_f32 v[148:149], v[56:57], v[104:105] op_sel_hi:[1,0]
	v_pk_fma_f32 v[142:143], v[64:65], v[142:143], v[76:77]
	v_pk_fma_f32 v[114:115], v[74:75], v[122:123], v[114:115]
	v_pk_mul_f32 v[116:117], v[118:119], v[116:117]
	v_pk_mul_f32 v[150:151], v[108:109], v[156:157] op_sel_hi:[0,1]
	v_pk_fma_f32 v[142:143], v[148:149], v[68:69], v[142:143]
	v_pk_mul_f32 v[114:115], v[114:115], v[116:117]
	v_pk_fma_f32 v[142:143], v[72:73], v[150:151], v[142:143]
	v_pk_mul_f32 v[144:145], v[146:147], v[144:145]
	v_cvt_pk_bf16_f32 v117, v114, v115
	v_mov_b64_e32 v[114:115], s[30:31]
	v_pk_mul_f32 v[142:143], v[142:143], v[144:145]
	v_mad_i64_i32 v[114:115], s[26:27], v102, s1, v[114:115]
	v_cvt_pk_bf16_f32 v116, v142, v143
	v_lshl_add_u64 v[114:115], v[170:171], 1, v[114:115]
	v_mov_b32_e32 v188, v116
	v_mov_b32_e32 v189, v117
.LBB0_1751:
	s_or_b64 exec, exec, s[24:25]
	v_mov_b32_dpp v125, v60 row_mirror row_mask:0xf bank_mask:0xf bound_ctrl:1
	v_mov_b32_dpp v126, v44 row_mirror row_mask:0xf bank_mask:0xf bound_ctrl:1
	v_mov_b32_dpp v120, v56 row_mirror row_mask:0xf bank_mask:0xf bound_ctrl:1
	v_mov_b32_dpp v142, v40 row_mirror row_mask:0xf bank_mask:0xf bound_ctrl:1
	v_mov_b32_dpp v127, v52 row_shr:1 row_mask:0xf bank_mask:0xf bound_ctrl:1
	v_mov_b32_dpp v140, v52 row_shl:1 row_mask:0xf bank_mask:0xf bound_ctrl:1
	v_mov_b32_dpp v122, v48 row_shr:1 row_mask:0xf bank_mask:0xf bound_ctrl:1
	v_mov_b32_dpp v145, v48 row_shl:1 row_mask:0xf bank_mask:0xf bound_ctrl:1
	v_mov_b32_dpp v141, v61 row_mirror row_mask:0xf bank_mask:0xf bound_ctrl:1
	v_mov_b32_dpp v143, v45 row_mirror row_mask:0xf bank_mask:0xf bound_ctrl:1
	v_mov_b32_dpp v123, v57 row_mirror row_mask:0xf bank_mask:0xf bound_ctrl:1
	v_mov_b32_dpp v147, v41 row_mirror row_mask:0xf bank_mask:0xf bound_ctrl:1
	v_mov_b32_dpp v144, v53 row_shr:1 row_mask:0xf bank_mask:0xf bound_ctrl:1
	v_mov_b32_dpp v146, v53 row_shl:1 row_mask:0xf bank_mask:0xf bound_ctrl:1
	v_mov_b32_dpp v124, v49 row_shr:1 row_mask:0xf bank_mask:0xf bound_ctrl:1
	v_mov_b32_dpp v148, v49 row_shl:1 row_mask:0xf bank_mask:0xf bound_ctrl:1
	v_mov_b32_dpp v60, v62 row_mirror row_mask:0xf bank_mask:0xf bound_ctrl:1
	v_mov_b32_dpp v62, v46 row_mirror row_mask:0xf bank_mask:0xf bound_ctrl:1
	v_mov_b32_dpp v56, v58 row_mirror row_mask:0xf bank_mask:0xf bound_ctrl:1
	v_mov_b32_dpp v115, v42 row_mirror row_mask:0xf bank_mask:0xf bound_ctrl:1
	v_mov_b32_dpp v61, v54 row_shr:1 row_mask:0xf bank_mask:0xf bound_ctrl:1
	v_mov_b32_dpp v113, v54 row_shl:1 row_mask:0xf bank_mask:0xf bound_ctrl:1
	v_mov_b32_dpp v57, v50 row_shr:1 row_mask:0xf bank_mask:0xf bound_ctrl:1
	v_mov_b32_dpp v117, v50 row_shl:1 row_mask:0xf bank_mask:0xf bound_ctrl:1
	v_mov_b32_dpp v63, v63 row_mirror row_mask:0xf bank_mask:0xf bound_ctrl:1
	v_mov_b32_dpp v116, v47 row_mirror row_mask:0xf bank_mask:0xf bound_ctrl:1
	v_mov_b32_dpp v58, v59 row_mirror row_mask:0xf bank_mask:0xf bound_ctrl:1
	v_mov_b32_dpp v119, v43 row_mirror row_mask:0xf bank_mask:0xf bound_ctrl:1
	v_mov_b32_dpp v114, v55 row_shr:1 row_mask:0xf bank_mask:0xf bound_ctrl:1
	v_mov_b32_dpp v118, v55 row_shl:1 row_mask:0xf bank_mask:0xf bound_ctrl:1
	v_mov_b32_dpp v59, v51 row_shr:1 row_mask:0xf bank_mask:0xf bound_ctrl:1
	v_mov_b32_dpp v121, v51 row_shl:1 row_mask:0xf bank_mask:0xf bound_ctrl:1
	v_cmp_lt_i32_e32 vcc, 46, v209
	s_mov_b64 s[26:27], 0
	s_and_saveexec_b64 s[24:25], vcc
	s_xor_b64 s[24:25], exec, s[24:25]
	s_and_b64 s[26:27], s[12:13], exec
	s_andn2_saveexec_b64 s[24:25], s[24:25]
	s_andn2_b64 s[26:27], s[26:27], exec
	s_and_b64 s[44:45], s[14:15], exec
	s_or_b64 s[26:27], s[26:27], s[44:45]
	s_or_b64 exec, exec, s[24:25]
	v_cndmask_b32_e64 v110, v97, v110, s[4:5]
	v_cndmask_b32_e64 v112, v101, v112, s[6:7]
	v_add_u32_e32 v97, s42, v213
	s_and_saveexec_b64 s[24:25], s[26:27]
	s_cbranch_execz .LBB0_1757
	v_cndmask_b32_e64 v149, v147, v148, s[6:7]
	v_cndmask_b32_e64 v148, v142, v145, s[6:7]
	v_cndmask_b32_e64 v142, v126, v140, s[6:7]
	v_cndmask_b32_e64 v141, v141, v144, s[4:5]
	v_cndmask_b32_e64 v140, v125, v127, s[4:5]
	v_pk_mul_f32 v[140:141], v[110:111], v[140:141] op_sel_hi:[0,1]
	v_cndmask_b32_e64 v143, v143, v146, s[6:7]
	v_pk_mul_f32 v[146:147], v[52:53], v[100:101] op_sel_hi:[1,0]
	s_waitcnt vmcnt(4)
	v_pk_fma_f32 v[140:141], v[80:81], v[140:141], v[92:93]
	v_pk_mul_f32 v[126:127], v[112:113], v[142:143] op_sel_hi:[0,1]
	v_pk_fma_f32 v[140:141], v[146:147], v[84:85], v[140:141]
	v_cndmask_b32_e64 v123, v123, v124, s[4:5]
	v_pk_fma_f32 v[126:127], v[88:89], v[126:127], v[140:141]
	v_cndmask_b32_e64 v122, v120, v122, s[4:5]
	v_mul_f32_e32 v125, 0xbfb8aa3b, v126
	v_exp_f32_e32 v125, v125
	v_mul_f32_e32 v124, 0xbfb8aa3b, v127
	v_cndmask_b32_e64 v63, v63, v114, s[4:5]
	v_cndmask_b32_e64 v121, v119, v121, s[6:7]
	v_add_f32_e32 v120, 1.0, v125
	v_exp_f32_e32 v125, v124
	v_rcp_f32_e32 v124, v120
	v_cndmask_b32_e64 v59, v58, v59, s[4:5]
	v_cndmask_b32_e64 v58, v56, v57, s[4:5]
	v_add_f32_e32 v120, 1.0, v125
	v_rcp_f32_e32 v125, v120
	v_cndmask_b32_e64 v120, v115, v117, s[6:7]
	v_cndmask_b32_e64 v117, v116, v118, s[6:7]
	v_cndmask_b32_e64 v116, v62, v113, s[6:7]
	v_cndmask_b32_e64 v62, v60, v61, s[4:5]
	v_pk_mul_f32 v[62:63], v[110:111], v[62:63] op_sel_hi:[0,1]
	v_pk_mul_f32 v[118:119], v[54:55], v[100:101] op_sel_hi:[1,0]
	v_pk_fma_f32 v[62:63], v[82:83], v[62:63], v[94:95]
	v_pk_mul_f32 v[60:61], v[112:113], v[116:117] op_sel_hi:[0,1]
	v_pk_fma_f32 v[62:63], v[118:119], v[86:87], v[62:63]
	v_pk_mul_f32 v[142:143], v[112:113], v[148:149] op_sel_hi:[0,1]
	v_pk_fma_f32 v[60:61], v[90:91], v[60:61], v[62:63]
	v_pk_mul_f32 v[58:59], v[110:111], v[58:59] op_sel_hi:[0,1]
	v_mul_f32_e32 v62, 0xbfb8aa3b, v60
	v_mul_f32_e32 v57, 0xbfb8aa3b, v61
	v_exp_f32_e32 v113, v62
	v_exp_f32_e32 v57, v57
	v_pk_mul_f32 v[62:63], v[50:51], v[100:101] op_sel_hi:[1,0]
	s_waitcnt vmcnt(0)
	v_pk_fma_f32 v[58:59], v[66:67], v[58:59], v[78:79]
	v_add_f32_e32 v56, 1.0, v113
	v_add_f32_e32 v57, 1.0, v57
	v_rcp_f32_e32 v56, v56
	v_rcp_f32_e32 v57, v57
	v_pk_mul_f32 v[122:123], v[110:111], v[122:123] op_sel_hi:[0,1]
	v_pk_mul_f32 v[114:115], v[112:113], v[120:121] op_sel_hi:[0,1]
	v_pk_fma_f32 v[58:59], v[62:63], v[70:71], v[58:59]
	v_pk_mul_f32 v[140:141], v[48:49], v[100:101] op_sel_hi:[1,0]
	v_pk_fma_f32 v[122:123], v[64:65], v[122:123], v[76:77]
	v_pk_fma_f32 v[58:59], v[74:75], v[114:115], v[58:59]
	v_pk_mul_f32 v[56:57], v[60:61], v[56:57]
	v_pk_fma_f32 v[122:123], v[140:141], v[68:69], v[122:123]
	v_pk_mul_f32 v[56:57], v[58:59], v[56:57]
	v_pk_fma_f32 v[122:123], v[72:73], v[142:143], v[122:123]
	v_pk_mul_f32 v[124:125], v[126:127], v[124:125]
	v_cvt_pk_bf16_f32 v59, v56, v57
	v_mov_b64_e32 v[56:57], s[30:31]
	v_pk_mul_f32 v[122:123], v[122:123], v[124:125]
	v_mad_i64_i32 v[56:57], s[26:27], v97, s1, v[56:57]
	v_cvt_pk_bf16_f32 v58, v122, v123
	v_lshl_add_u64 v[56:57], v[170:171], 1, v[56:57]
	v_mov_b32_e32 v190, v58
	v_mov_b32_e32 v191, v59
.LBB0_1757:
	s_or_b64 exec, exec, s[24:25]
	v_mov_b32_dpp v119, v52 row_mirror row_mask:0xf bank_mask:0xf bound_ctrl:1
	v_mov_b32_dpp v120, v36 row_mirror row_mask:0xf bank_mask:0xf bound_ctrl:1
	v_mov_b32_dpp v63, v48 row_mirror row_mask:0xf bank_mask:0xf bound_ctrl:1
	v_mov_b32_dpp v124, v32 row_mirror row_mask:0xf bank_mask:0xf bound_ctrl:1
	v_mov_b32_dpp v121, v44 row_shr:1 row_mask:0xf bank_mask:0xf bound_ctrl:1
	v_mov_b32_dpp v122, v44 row_shl:1 row_mask:0xf bank_mask:0xf bound_ctrl:1
	v_mov_b32_dpp v115, v40 row_shr:1 row_mask:0xf bank_mask:0xf bound_ctrl:1
	v_mov_b32_dpp v127, v40 row_shl:1 row_mask:0xf bank_mask:0xf bound_ctrl:1
	v_mov_b32_dpp v123, v53 row_mirror row_mask:0xf bank_mask:0xf bound_ctrl:1
	v_mov_b32_dpp v125, v37 row_mirror row_mask:0xf bank_mask:0xf bound_ctrl:1
	v_mov_b32_dpp v117, v49 row_mirror row_mask:0xf bank_mask:0xf bound_ctrl:1
	v_mov_b32_dpp v141, v33 row_mirror row_mask:0xf bank_mask:0xf bound_ctrl:1
	v_mov_b32_dpp v126, v45 row_shr:1 row_mask:0xf bank_mask:0xf bound_ctrl:1
	v_mov_b32_dpp v140, v45 row_shl:1 row_mask:0xf bank_mask:0xf bound_ctrl:1
	v_mov_b32_dpp v118, v41 row_shr:1 row_mask:0xf bank_mask:0xf bound_ctrl:1
	v_mov_b32_dpp v142, v41 row_shl:1 row_mask:0xf bank_mask:0xf bound_ctrl:1
	v_mov_b32_dpp v52, v54 row_mirror row_mask:0xf bank_mask:0xf bound_ctrl:1
	v_mov_b32_dpp v54, v38 row_mirror row_mask:0xf bank_mask:0xf bound_ctrl:1
	v_mov_b32_dpp v48, v50 row_mirror row_mask:0xf bank_mask:0xf bound_ctrl:1
	v_mov_b32_dpp v58, v34 row_mirror row_mask:0xf bank_mask:0xf bound_ctrl:1
	v_mov_b32_dpp v53, v46 row_shr:1 row_mask:0xf bank_mask:0xf bound_ctrl:1
	v_mov_b32_dpp v56, v46 row_shl:1 row_mask:0xf bank_mask:0xf bound_ctrl:1
	v_mov_b32_dpp v49, v42 row_shr:1 row_mask:0xf bank_mask:0xf bound_ctrl:1
	v_mov_b32_dpp v60, v42 row_shl:1 row_mask:0xf bank_mask:0xf bound_ctrl:1
	v_mov_b32_dpp v55, v55 row_mirror row_mask:0xf bank_mask:0xf bound_ctrl:1
	v_mov_b32_dpp v59, v39 row_mirror row_mask:0xf bank_mask:0xf bound_ctrl:1
	v_mov_b32_dpp v50, v51 row_mirror row_mask:0xf bank_mask:0xf bound_ctrl:1
	v_mov_b32_dpp v62, v35 row_mirror row_mask:0xf bank_mask:0xf bound_ctrl:1
	v_mov_b32_dpp v57, v47 row_shr:1 row_mask:0xf bank_mask:0xf bound_ctrl:1
	v_mov_b32_dpp v61, v47 row_shl:1 row_mask:0xf bank_mask:0xf bound_ctrl:1
	v_mov_b32_dpp v51, v43 row_shr:1 row_mask:0xf bank_mask:0xf bound_ctrl:1
	v_mov_b32_dpp v113, v43 row_shl:1 row_mask:0xf bank_mask:0xf bound_ctrl:1
	v_cmp_lt_i32_e32 vcc, 30, v209
	s_mov_b64 s[26:27], 0
	s_and_saveexec_b64 s[24:25], vcc
	s_xor_b64 s[24:25], exec, s[24:25]
	s_and_b64 s[26:27], s[16:17], exec
	s_andn2_saveexec_b64 s[24:25], s[24:25]
	s_andn2_b64 s[26:27], s[26:27], exec
	s_and_b64 s[44:45], s[18:19], exec
	s_or_b64 s[26:27], s[26:27], s[44:45]
	s_or_b64 exec, exec, s[24:25]
	v_cndmask_b32_e64 v114, v99, v109, s[4:5]
	v_cndmask_b32_e64 v116, v103, v111, s[6:7]
	v_add_u32_e32 v99, s42, v215
	s_and_saveexec_b64 s[24:25], s[26:27]
	s_cbranch_execz .LBB0_1763
	v_cndmask_b32_e64 v143, v141, v142, s[6:7]
	v_cndmask_b32_e64 v142, v124, v127, s[6:7]
	v_cndmask_b32_e64 v124, v120, v122, s[6:7]
	v_cndmask_b32_e64 v123, v123, v126, s[4:5]
	v_cndmask_b32_e64 v122, v119, v121, s[4:5]
	v_pk_mul_f32 v[122:123], v[114:115], v[122:123] op_sel_hi:[0,1]
	v_cndmask_b32_e64 v125, v125, v140, s[6:7]
	v_pk_mul_f32 v[140:141], v[44:45], v[98:99] op_sel_hi:[1,0]
	s_waitcnt vmcnt(4)
	v_pk_fma_f32 v[122:123], v[80:81], v[122:123], v[92:93]
	v_pk_mul_f32 v[120:121], v[116:117], v[124:125] op_sel_hi:[0,1]
	v_pk_fma_f32 v[122:123], v[140:141], v[84:85], v[122:123]
	v_cndmask_b32_e64 v119, v117, v118, s[4:5]
	v_pk_fma_f32 v[120:121], v[88:89], v[120:121], v[122:123]
	v_cndmask_b32_e64 v118, v63, v115, s[4:5]
	v_mul_f32_e32 v109, 0xbfb8aa3b, v120
	v_exp_f32_e32 v109, v109
	v_cndmask_b32_e64 v55, v55, v57, s[4:5]
	v_cndmask_b32_e64 v59, v59, v61, s[6:7]
	v_cndmask_b32_e64 v51, v50, v51, s[4:5]
	v_add_f32_e32 v63, 1.0, v109
	v_mul_f32_e32 v109, 0xbfb8aa3b, v121
	v_exp_f32_e32 v109, v109
	v_rcp_f32_e32 v124, v63
	v_cndmask_b32_e64 v50, v48, v49, s[4:5]
	v_pk_mul_f32 v[50:51], v[114:115], v[50:51] op_sel_hi:[0,1]
	v_add_f32_e32 v63, 1.0, v109
	v_rcp_f32_e32 v125, v63
	v_cndmask_b32_e64 v63, v62, v113, s[6:7]
	v_cndmask_b32_e64 v62, v58, v60, s[6:7]
	v_cndmask_b32_e64 v58, v54, v56, s[6:7]
	v_cndmask_b32_e64 v54, v52, v53, s[4:5]
	v_pk_mul_f32 v[54:55], v[114:115], v[54:55] op_sel_hi:[0,1]
	v_pk_mul_f32 v[60:61], v[46:47], v[98:99] op_sel_hi:[1,0]
	v_pk_fma_f32 v[54:55], v[82:83], v[54:55], v[94:95]
	v_pk_mul_f32 v[52:53], v[116:117], v[58:59] op_sel_hi:[0,1]
	v_pk_fma_f32 v[54:55], v[60:61], v[86:87], v[54:55]
	s_waitcnt vmcnt(0)
	v_pk_fma_f32 v[50:51], v[66:67], v[50:51], v[78:79]
	v_pk_fma_f32 v[52:53], v[90:91], v[52:53], v[54:55]
	v_pk_mul_f32 v[118:119], v[114:115], v[118:119] op_sel_hi:[0,1]
	v_mul_f32_e32 v54, 0xbfb8aa3b, v52
	v_mul_f32_e32 v49, 0xbfb8aa3b, v53
	v_exp_f32_e32 v56, v54
	v_exp_f32_e32 v49, v49
	v_pk_mul_f32 v[54:55], v[42:43], v[98:99] op_sel_hi:[1,0]
	v_pk_mul_f32 v[122:123], v[40:41], v[98:99] op_sel_hi:[1,0]
	v_add_f32_e32 v48, 1.0, v56
	v_add_f32_e32 v49, 1.0, v49
	v_rcp_f32_e32 v48, v48
	v_rcp_f32_e32 v49, v49
	v_pk_mul_f32 v[56:57], v[116:117], v[62:63] op_sel_hi:[0,1]
	v_pk_fma_f32 v[50:51], v[54:55], v[70:71], v[50:51]
	v_pk_fma_f32 v[118:119], v[64:65], v[118:119], v[76:77]
	v_pk_fma_f32 v[50:51], v[74:75], v[56:57], v[50:51]
	v_pk_mul_f32 v[48:49], v[52:53], v[48:49]
	v_pk_mul_f32 v[126:127], v[116:117], v[142:143] op_sel_hi:[0,1]
	v_pk_fma_f32 v[118:119], v[122:123], v[68:69], v[118:119]
	v_pk_mul_f32 v[48:49], v[50:51], v[48:49]
	v_pk_fma_f32 v[118:119], v[72:73], v[126:127], v[118:119]
	v_pk_mul_f32 v[120:121], v[120:121], v[124:125]
	v_cvt_pk_bf16_f32 v51, v48, v49
	v_mov_b64_e32 v[48:49], s[30:31]
	v_pk_mul_f32 v[118:119], v[118:119], v[120:121]
	v_mad_i64_i32 v[48:49], s[26:27], v99, s1, v[48:49]
	v_cvt_pk_bf16_f32 v50, v118, v119
	v_lshl_add_u64 v[48:49], v[170:171], 1, v[48:49]
	v_mov_b32_e32 v192, v50
	v_mov_b32_e32 v193, v51
.LBB0_1763:
	s_or_b64 exec, exec, s[24:25]
	v_mov_b32_dpp v60, v44 row_mirror row_mask:0xf bank_mask:0xf bound_ctrl:1
	v_mov_b32_dpp v61, v36 row_mirror row_mask:0xf bank_mask:0xf bound_ctrl:1
	v_mov_b32_dpp v55, v40 row_mirror row_mask:0xf bank_mask:0xf bound_ctrl:1
	v_mov_b32_dpp v111, v32 row_mirror row_mask:0xf bank_mask:0xf bound_ctrl:1
	v_mov_b32_dpp v62, v36 row_shr:1 row_mask:0xf bank_mask:0xf bound_ctrl:1
	v_mov_b32_dpp v63, v36 row_shl:1 row_mask:0xf bank_mask:0xf bound_ctrl:1
	v_mov_b32_dpp v57, v32 row_shr:1 row_mask:0xf bank_mask:0xf bound_ctrl:1
	v_mov_b32_dpp v117, v32 row_shl:1 row_mask:0xf bank_mask:0xf bound_ctrl:1
	v_mov_b32_dpp v109, v45 row_mirror row_mask:0xf bank_mask:0xf bound_ctrl:1
	v_mov_b32_dpp v113, v37 row_mirror row_mask:0xf bank_mask:0xf bound_ctrl:1
	v_mov_b32_dpp v58, v41 row_mirror row_mask:0xf bank_mask:0xf bound_ctrl:1
	v_mov_b32_dpp v121, v33 row_mirror row_mask:0xf bank_mask:0xf bound_ctrl:1
	v_mov_b32_dpp v115, v37 row_shr:1 row_mask:0xf bank_mask:0xf bound_ctrl:1
	v_mov_b32_dpp v119, v37 row_shl:1 row_mask:0xf bank_mask:0xf bound_ctrl:1
	v_mov_b32_dpp v59, v33 row_shr:1 row_mask:0xf bank_mask:0xf bound_ctrl:1
	v_mov_b32_dpp v122, v33 row_shl:1 row_mask:0xf bank_mask:0xf bound_ctrl:1
	v_mov_b32_dpp v44, v46 row_mirror row_mask:0xf bank_mask:0xf bound_ctrl:1
	v_mov_b32_dpp v46, v38 row_mirror row_mask:0xf bank_mask:0xf bound_ctrl:1
	v_mov_b32_dpp v40, v42 row_mirror row_mask:0xf bank_mask:0xf bound_ctrl:1
	v_mov_b32_dpp v50, v34 row_mirror row_mask:0xf bank_mask:0xf bound_ctrl:1
	v_mov_b32_dpp v45, v38 row_shr:1 row_mask:0xf bank_mask:0xf bound_ctrl:1
	v_mov_b32_dpp v48, v38 row_shl:1 row_mask:0xf bank_mask:0xf bound_ctrl:1
	v_mov_b32_dpp v41, v34 row_shr:1 row_mask:0xf bank_mask:0xf bound_ctrl:1
	v_mov_b32_dpp v52, v34 row_shl:1 row_mask:0xf bank_mask:0xf bound_ctrl:1
	v_mov_b32_dpp v47, v47 row_mirror row_mask:0xf bank_mask:0xf bound_ctrl:1
	v_mov_b32_dpp v51, v39 row_mirror row_mask:0xf bank_mask:0xf bound_ctrl:1
	v_mov_b32_dpp v42, v43 row_mirror row_mask:0xf bank_mask:0xf bound_ctrl:1
	v_mov_b32_dpp v54, v35 row_mirror row_mask:0xf bank_mask:0xf bound_ctrl:1
	v_mov_b32_dpp v49, v39 row_shr:1 row_mask:0xf bank_mask:0xf bound_ctrl:1
	v_mov_b32_dpp v53, v39 row_shl:1 row_mask:0xf bank_mask:0xf bound_ctrl:1
	v_mov_b32_dpp v43, v35 row_shr:1 row_mask:0xf bank_mask:0xf bound_ctrl:1
	v_mov_b32_dpp v56, v35 row_shl:1 row_mask:0xf bank_mask:0xf bound_ctrl:1
	v_cmp_lt_i32_e32 vcc, 14, v209
	s_mov_b64 s[26:27], 0
	s_and_saveexec_b64 s[24:25], vcc
	s_xor_b64 s[24:25], exec, s[24:25]
	s_and_b64 s[26:27], s[20:21], exec
	s_andn2_saveexec_b64 s[24:25], s[24:25]
	s_andn2_b64 s[26:27], s[26:27], exec
	s_and_b64 s[44:45], s[22:23], exec
	s_or_b64 s[26:27], s[26:27], s[44:45]
	s_or_b64 exec, exec, s[24:25]
	v_cndmask_b32_e64 v118, v101, v105, s[4:5]
	v_cndmask_b32_e64 v120, v103, v107, s[6:7]
	v_add_u32_e32 v101, s42, v217
	s_and_saveexec_b64 s[24:25], s[26:27]
	s_cbranch_execz .LBB0_1769
	v_cndmask_b32_e64 v124, v61, v63, s[6:7]
	v_cndmask_b32_e64 v61, v109, v115, s[4:5]
	v_cndmask_b32_e64 v60, v60, v62, s[4:5]
	v_pk_mul_f32 v[60:61], v[118:119], v[60:61] op_sel_hi:[0,1]
	v_cndmask_b32_e64 v125, v113, v119, s[6:7]
	v_pk_mul_f32 v[36:37], v[36:37], v[96:97] op_sel_hi:[1,0]
	s_waitcnt vmcnt(4)
	v_pk_fma_f32 v[60:61], v[80:81], v[60:61], v[92:93]
	v_pk_mul_f32 v[62:63], v[120:121], v[124:125] op_sel_hi:[0,1]
	v_pk_fma_f32 v[36:37], v[36:37], v[84:85], v[60:61]
	v_cndmask_b32_e64 v59, v58, v59, s[4:5]
	v_pk_fma_f32 v[36:37], v[88:89], v[62:63], v[36:37]
	v_cndmask_b32_e64 v58, v55, v57, s[4:5]
	v_mul_f32_e32 v60, 0xbfb8aa3b, v36
	v_exp_f32_e32 v60, v60
	v_mul_f32_e32 v57, 0xbfb8aa3b, v37
	v_exp_f32_e32 v57, v57
	v_pk_mul_f32 v[58:59], v[118:119], v[58:59] op_sel_hi:[0,1]
	v_add_f32_e32 v55, 1.0, v60
	v_rcp_f32_e32 v60, v55
	v_add_f32_e32 v55, 1.0, v57
	v_rcp_f32_e32 v61, v55
	v_cndmask_b32_e64 v123, v121, v122, s[6:7]
	v_cndmask_b32_e64 v122, v111, v117, s[6:7]
	v_pk_mul_f32 v[32:33], v[32:33], v[96:97] op_sel_hi:[1,0]
	s_waitcnt vmcnt(0)
	v_pk_fma_f32 v[58:59], v[64:65], v[58:59], v[76:77]
	v_pk_mul_f32 v[62:63], v[120:121], v[122:123] op_sel_hi:[0,1]
	v_pk_fma_f32 v[32:33], v[32:33], v[68:69], v[58:59]
	v_pk_mul_f32 v[36:37], v[36:37], v[60:61]
	v_pk_fma_f32 v[32:33], v[72:73], v[62:63], v[32:33]
	v_cndmask_b32_e64 v47, v47, v49, s[4:5]
	v_pk_mul_f32 v[32:33], v[32:33], v[36:37]
	v_cndmask_b32_e64 v36, v50, v52, s[6:7]
	v_cndmask_b32_e64 v50, v46, v48, s[6:7]
	v_cndmask_b32_e64 v46, v44, v45, s[4:5]
	v_pk_mul_f32 v[46:47], v[118:119], v[46:47] op_sel_hi:[0,1]
	v_cndmask_b32_e64 v51, v51, v53, s[6:7]
	v_pk_mul_f32 v[38:39], v[38:39], v[96:97] op_sel_hi:[1,0]
	v_pk_fma_f32 v[46:47], v[82:83], v[46:47], v[94:95]
	v_pk_mul_f32 v[44:45], v[120:121], v[50:51] op_sel_hi:[0,1]
	v_pk_fma_f32 v[38:39], v[38:39], v[86:87], v[46:47]
	v_cndmask_b32_e64 v43, v42, v43, s[4:5]
	v_pk_fma_f32 v[38:39], v[90:91], v[44:45], v[38:39]
	v_cndmask_b32_e64 v42, v40, v41, s[4:5]
	v_mul_f32_e32 v44, 0xbfb8aa3b, v38
	v_mul_f32_e32 v41, 0xbfb8aa3b, v39
	v_exp_f32_e32 v44, v44
	v_exp_f32_e32 v41, v41
	v_pk_mul_f32 v[42:43], v[118:119], v[42:43] op_sel_hi:[0,1]
	v_cndmask_b32_e64 v37, v54, v56, s[6:7]
	v_add_f32_e32 v40, 1.0, v44
	v_add_f32_e32 v41, 1.0, v41
	v_rcp_f32_e32 v40, v40
	v_rcp_f32_e32 v41, v41
	v_pk_mul_f32 v[34:35], v[34:35], v[96:97] op_sel_hi:[1,0]
	v_pk_fma_f32 v[42:43], v[66:67], v[42:43], v[78:79]
	v_pk_mul_f32 v[36:37], v[120:121], v[36:37] op_sel_hi:[0,1]
	v_pk_fma_f32 v[34:35], v[34:35], v[70:71], v[42:43]
	v_cvt_pk_bf16_f32 v32, v32, v33
	v_pk_fma_f32 v[34:35], v[74:75], v[36:37], v[34:35]
	v_pk_mul_f32 v[36:37], v[38:39], v[40:41]
	s_nop 0
	v_pk_mul_f32 v[34:35], v[34:35], v[36:37]
	s_nop 0
	v_cvt_pk_bf16_f32 v33, v34, v35
	v_mov_b64_e32 v[34:35], s[30:31]
	v_mad_i64_i32 v[34:35], s[26:27], v101, s1, v[34:35]
	v_lshl_add_u64 v[34:35], v[170:171], 1, v[34:35]
	v_mov_b32_e32 v194, v32
	v_mov_b32_e32 v195, v33

.LBB0_1772:
	v_cndmask_b32_e64 v95, v94, v95, s[6:7]
	v_cndmask_b32_e64 v94, v89, v92, s[6:7]
	v_cndmask_b32_e64 v92, v85, v87, s[6:7]
	v_cndmask_b32_e64 v85, v88, v91, s[4:5]
	v_cndmask_b32_e64 v84, v84, v86, s[4:5]
	v_pk_mul_f32 v[84:85], v[106:107], v[84:85] op_sel_hi:[0,1]
	v_cndmask_b32_e64 v93, v90, v93, s[6:7]
	v_pk_mul_f32 v[122:123], v[28:29], v[104:105] op_sel_hi:[1,0]
	s_waitcnt vmcnt(4)
	v_pk_fma_f32 v[84:85], v[48:49], v[84:85], v[60:61]
	v_pk_mul_f32 v[86:87], v[108:109], v[92:93] op_sel_hi:[0,1]
	v_pk_fma_f32 v[84:85], v[122:123], v[52:53], v[84:85]
	v_cndmask_b32_e64 v83, v82, v83, s[4:5]
	v_pk_fma_f32 v[84:85], v[56:57], v[86:87], v[84:85]
	v_cndmask_b32_e64 v82, v79, v81, s[4:5]
	v_mul_f32_e32 v86, 0xbfb8aa3b, v84
	v_exp_f32_e32 v88, v86
	v_mul_f32_e32 v81, 0xbfb8aa3b, v85
	v_exp_f32_e32 v81, v81
	v_cndmask_b32_e64 v71, v71, v73, s[4:5]
	v_add_f32_e32 v79, 1.0, v88
	v_rcp_f32_e32 v88, v79
	v_add_f32_e32 v79, 1.0, v81
	v_rcp_f32_e32 v89, v79
	v_cndmask_b32_e64 v79, v78, v80, s[6:7]
	v_cndmask_b32_e64 v78, v74, v76, s[6:7]
	v_cndmask_b32_e64 v74, v70, v72, s[6:7]
	v_cndmask_b32_e64 v70, v68, v69, s[4:5]
	v_pk_mul_f32 v[70:71], v[106:107], v[70:71] op_sel_hi:[0,1]
	v_cndmask_b32_e64 v75, v75, v77, s[6:7]
	v_pk_mul_f32 v[76:77], v[30:31], v[104:105] op_sel_hi:[1,0]
	v_pk_fma_f32 v[70:71], v[50:51], v[70:71], v[62:63]
	v_pk_mul_f32 v[68:69], v[108:109], v[74:75] op_sel_hi:[0,1]
	v_pk_fma_f32 v[70:71], v[76:77], v[54:55], v[70:71]
	v_cndmask_b32_e64 v67, v66, v67, s[4:5]
	v_pk_fma_f32 v[68:69], v[58:59], v[68:69], v[70:71]
	v_cndmask_b32_e64 v66, v64, v65, s[4:5]
	v_mul_f32_e32 v70, 0xbfb8aa3b, v68
	v_mul_f32_e32 v65, 0xbfb8aa3b, v69
	v_exp_f32_e32 v72, v70
	v_exp_f32_e32 v65, v65
	v_pk_mul_f32 v[66:67], v[106:107], v[66:67] op_sel_hi:[0,1]
	v_pk_mul_f32 v[70:71], v[26:27], v[104:105] op_sel_hi:[1,0]
	v_add_f32_e32 v64, 1.0, v72
	v_add_f32_e32 v65, 1.0, v65
	v_rcp_f32_e32 v64, v64
	v_rcp_f32_e32 v65, v65
	s_waitcnt vmcnt(0)
	v_pk_fma_f32 v[66:67], v[34:35], v[66:67], v[46:47]
	v_pk_mul_f32 v[82:83], v[106:107], v[82:83] op_sel_hi:[0,1]
	v_pk_mul_f32 v[72:73], v[108:109], v[78:79] op_sel_hi:[0,1]
	v_pk_fma_f32 v[66:67], v[70:71], v[38:39], v[66:67]
	v_pk_mul_f32 v[86:87], v[24:25], v[104:105] op_sel_hi:[1,0]
	v_pk_fma_f32 v[82:83], v[32:33], v[82:83], v[44:45]
	v_pk_fma_f32 v[66:67], v[42:43], v[72:73], v[66:67]
	v_pk_mul_f32 v[64:65], v[68:69], v[64:65]
	v_pk_mul_f32 v[90:91], v[108:109], v[94:95] op_sel_hi:[0,1]
	v_pk_fma_f32 v[82:83], v[86:87], v[36:37], v[82:83]
	v_pk_mul_f32 v[64:65], v[66:67], v[64:65]
	v_pk_fma_f32 v[82:83], v[40:41], v[90:91], v[82:83]
	v_pk_mul_f32 v[84:85], v[84:85], v[88:89]
	v_cvt_pk_bf16_f32 v67, v64, v65
	v_mov_b64_e32 v[64:65], s[30:31]
	v_pk_mul_f32 v[82:83], v[82:83], v[84:85]
	v_mad_i64_i32 v[64:65], s[10:11], v102, s1, v[64:65]
	v_cvt_pk_bf16_f32 v66, v82, v83
	v_lshl_add_u64 v[64:65], v[170:171], 1, v[64:65]
	v_mov_b32_e32 v178, v188
	v_mov_b32_e32 v179, v189
	v_mov_b32_e32 v180, v66
	v_mov_b32_e32 v181, v67
	global_store_dwordx4 v[64:65], v[178:181], off

.LBB0_1776:
	v_cndmask_b32_e64 v87, v86, v87, s[6:7]
	v_cndmask_b32_e64 v86, v81, v84, s[6:7]
	v_cndmask_b32_e64 v84, v77, v79, s[6:7]
	v_cndmask_b32_e64 v77, v80, v83, s[4:5]
	v_cndmask_b32_e64 v76, v76, v78, s[4:5]
	v_pk_mul_f32 v[76:77], v[110:111], v[76:77] op_sel_hi:[0,1]
	v_cndmask_b32_e64 v85, v82, v85, s[6:7]
	v_pk_mul_f32 v[88:89], v[20:21], v[100:101] op_sel_hi:[1,0]
	s_waitcnt vmcnt(4)
	v_pk_fma_f32 v[76:77], v[48:49], v[76:77], v[60:61]
	v_pk_mul_f32 v[78:79], v[112:113], v[84:85] op_sel_hi:[0,1]
	v_pk_fma_f32 v[76:77], v[88:89], v[52:53], v[76:77]
	v_cndmask_b32_e64 v75, v74, v75, s[4:5]
	v_pk_fma_f32 v[76:77], v[56:57], v[78:79], v[76:77]
	v_cndmask_b32_e64 v74, v71, v73, s[4:5]
	v_mul_f32_e32 v78, 0xbfb8aa3b, v76
	v_exp_f32_e32 v80, v78
	v_mul_f32_e32 v73, 0xbfb8aa3b, v77
	v_exp_f32_e32 v73, v73
	v_cndmask_b32_e64 v31, v31, v65, s[4:5]
	v_add_f32_e32 v71, 1.0, v80
	v_rcp_f32_e32 v80, v71
	v_add_f32_e32 v71, 1.0, v73
	v_rcp_f32_e32 v81, v71
	v_cndmask_b32_e64 v71, v70, v72, s[6:7]
	v_cndmask_b32_e64 v70, v66, v68, s[6:7]
	v_cndmask_b32_e64 v66, v30, v64, s[6:7]
	v_cndmask_b32_e64 v30, v28, v29, s[4:5]
	v_pk_mul_f32 v[30:31], v[110:111], v[30:31] op_sel_hi:[0,1]
	v_cndmask_b32_e64 v67, v67, v69, s[6:7]
	v_pk_mul_f32 v[68:69], v[22:23], v[100:101] op_sel_hi:[1,0]
	v_pk_fma_f32 v[30:31], v[50:51], v[30:31], v[62:63]
	v_pk_mul_f32 v[28:29], v[112:113], v[66:67] op_sel_hi:[0,1]
	v_pk_fma_f32 v[30:31], v[68:69], v[54:55], v[30:31]
	v_cndmask_b32_e64 v27, v26, v27, s[4:5]
	v_pk_fma_f32 v[28:29], v[58:59], v[28:29], v[30:31]
	v_cndmask_b32_e64 v26, v24, v25, s[4:5]
	v_mul_f32_e32 v30, 0xbfb8aa3b, v28
	v_mul_f32_e32 v25, 0xbfb8aa3b, v29
	v_exp_f32_e32 v64, v30
	v_exp_f32_e32 v25, v25
	v_pk_mul_f32 v[26:27], v[110:111], v[26:27] op_sel_hi:[0,1]
	v_pk_mul_f32 v[30:31], v[18:19], v[100:101] op_sel_hi:[1,0]
	v_add_f32_e32 v24, 1.0, v64
	v_add_f32_e32 v25, 1.0, v25
	v_rcp_f32_e32 v24, v24
	v_rcp_f32_e32 v25, v25
	s_waitcnt vmcnt(0)
	v_pk_fma_f32 v[26:27], v[34:35], v[26:27], v[46:47]
	v_pk_mul_f32 v[74:75], v[110:111], v[74:75] op_sel_hi:[0,1]
	v_pk_mul_f32 v[64:65], v[112:113], v[70:71] op_sel_hi:[0,1]
	v_pk_fma_f32 v[26:27], v[30:31], v[38:39], v[26:27]
	v_pk_mul_f32 v[78:79], v[16:17], v[100:101] op_sel_hi:[1,0]
	v_pk_fma_f32 v[74:75], v[32:33], v[74:75], v[44:45]
	v_pk_fma_f32 v[26:27], v[42:43], v[64:65], v[26:27]
	v_pk_mul_f32 v[24:25], v[28:29], v[24:25]
	v_pk_mul_f32 v[82:83], v[112:113], v[86:87] op_sel_hi:[0,1]
	v_pk_fma_f32 v[74:75], v[78:79], v[36:37], v[74:75]
	v_pk_mul_f32 v[24:25], v[26:27], v[24:25]
	v_pk_fma_f32 v[74:75], v[40:41], v[82:83], v[74:75]
	v_pk_mul_f32 v[76:77], v[76:77], v[80:81]
	v_cvt_pk_bf16_f32 v27, v24, v25
	v_mov_b64_e32 v[24:25], s[30:31]
	v_pk_mul_f32 v[74:75], v[74:75], v[76:77]
	v_mad_i64_i32 v[24:25], s[10:11], v97, s1, v[24:25]
	v_cvt_pk_bf16_f32 v26, v74, v75
	v_lshl_add_u64 v[24:25], v[170:171], 1, v[24:25]
	v_mov_b32_e32 v178, v190
	v_mov_b32_e32 v179, v191
	v_mov_b32_e32 v180, v26
	v_mov_b32_e32 v181, v27
	global_store_dwordx4 v[24:25], v[178:181], off

.LBB0_1780:
	v_cndmask_b32_e64 v79, v78, v79, s[6:7]
	v_cndmask_b32_e64 v78, v73, v76, s[6:7]
	v_cndmask_b32_e64 v76, v69, v71, s[6:7]
	v_cndmask_b32_e64 v69, v72, v75, s[4:5]
	v_cndmask_b32_e64 v68, v68, v70, s[4:5]
	v_pk_mul_f32 v[68:69], v[114:115], v[68:69] op_sel_hi:[0,1]
	v_cndmask_b32_e64 v77, v74, v77, s[6:7]
	v_pk_mul_f32 v[80:81], v[12:13], v[98:99] op_sel_hi:[1,0]
	s_waitcnt vmcnt(4)
	v_pk_fma_f32 v[68:69], v[48:49], v[68:69], v[60:61]
	v_pk_mul_f32 v[70:71], v[116:117], v[76:77] op_sel_hi:[0,1]
	v_pk_fma_f32 v[68:69], v[80:81], v[52:53], v[68:69]
	v_cndmask_b32_e64 v67, v66, v67, s[4:5]
	v_pk_fma_f32 v[68:69], v[56:57], v[70:71], v[68:69]
	v_cndmask_b32_e64 v66, v31, v65, s[4:5]
	v_mul_f32_e32 v70, 0xbfb8aa3b, v68
	v_exp_f32_e32 v72, v70
	v_mul_f32_e32 v65, 0xbfb8aa3b, v69
	v_exp_f32_e32 v65, v65
	v_cndmask_b32_e64 v23, v23, v25, s[4:5]
	v_add_f32_e32 v31, 1.0, v72
	v_rcp_f32_e32 v72, v31
	v_add_f32_e32 v31, 1.0, v65
	v_rcp_f32_e32 v73, v31
	v_cndmask_b32_e64 v31, v30, v64, s[6:7]
	v_cndmask_b32_e64 v30, v26, v28, s[6:7]
	v_cndmask_b32_e64 v26, v22, v24, s[6:7]
	v_cndmask_b32_e64 v22, v20, v21, s[4:5]
	v_pk_mul_f32 v[22:23], v[114:115], v[22:23] op_sel_hi:[0,1]
	v_cndmask_b32_e64 v27, v27, v29, s[6:7]
	v_pk_mul_f32 v[28:29], v[14:15], v[98:99] op_sel_hi:[1,0]
	v_pk_fma_f32 v[22:23], v[50:51], v[22:23], v[62:63]
	v_pk_mul_f32 v[20:21], v[116:117], v[26:27] op_sel_hi:[0,1]
	v_pk_fma_f32 v[22:23], v[28:29], v[54:55], v[22:23]
	v_cndmask_b32_e64 v19, v18, v19, s[4:5]
	v_pk_fma_f32 v[20:21], v[58:59], v[20:21], v[22:23]
	v_cndmask_b32_e64 v18, v16, v17, s[4:5]
	v_mul_f32_e32 v22, 0xbfb8aa3b, v20
	v_mul_f32_e32 v17, 0xbfb8aa3b, v21
	v_exp_f32_e32 v24, v22
	v_exp_f32_e32 v17, v17
	v_pk_mul_f32 v[18:19], v[114:115], v[18:19] op_sel_hi:[0,1]
	v_pk_mul_f32 v[22:23], v[10:11], v[98:99] op_sel_hi:[1,0]
	v_add_f32_e32 v16, 1.0, v24
	v_add_f32_e32 v17, 1.0, v17
	v_rcp_f32_e32 v16, v16
	v_rcp_f32_e32 v17, v17
	s_waitcnt vmcnt(0)
	v_pk_fma_f32 v[18:19], v[34:35], v[18:19], v[46:47]
	v_pk_mul_f32 v[66:67], v[114:115], v[66:67] op_sel_hi:[0,1]
	v_pk_mul_f32 v[24:25], v[116:117], v[30:31] op_sel_hi:[0,1]
	v_pk_fma_f32 v[18:19], v[22:23], v[38:39], v[18:19]
	v_pk_mul_f32 v[70:71], v[8:9], v[98:99] op_sel_hi:[1,0]
	v_pk_fma_f32 v[66:67], v[32:33], v[66:67], v[44:45]
	v_pk_fma_f32 v[18:19], v[42:43], v[24:25], v[18:19]
	v_pk_mul_f32 v[16:17], v[20:21], v[16:17]
	v_pk_mul_f32 v[74:75], v[116:117], v[78:79] op_sel_hi:[0,1]
	v_pk_fma_f32 v[66:67], v[70:71], v[36:37], v[66:67]
	v_pk_mul_f32 v[16:17], v[18:19], v[16:17]
	v_pk_fma_f32 v[66:67], v[40:41], v[74:75], v[66:67]
	v_pk_mul_f32 v[68:69], v[68:69], v[72:73]
	v_cvt_pk_bf16_f32 v19, v16, v17
	v_mov_b64_e32 v[16:17], s[30:31]
	v_pk_mul_f32 v[66:67], v[66:67], v[68:69]
	v_mad_i64_i32 v[16:17], s[10:11], v99, s1, v[16:17]
	v_cvt_pk_bf16_f32 v18, v66, v67
	v_lshl_add_u64 v[16:17], v[170:171], 1, v[16:17]
	v_mov_b32_e32 v178, v192
	v_mov_b32_e32 v179, v193
	v_mov_b32_e32 v180, v18
	v_mov_b32_e32 v181, v19
	global_store_dwordx4 v[16:17], v[178:181], off

.LBB0_1784:
	v_cndmask_b32_e64 v71, v70, v71, s[6:7]
	v_cndmask_b32_e64 v70, v65, v68, s[6:7]
	v_cndmask_b32_e64 v68, v29, v31, s[6:7]
	v_cndmask_b32_e64 v29, v64, v67, s[4:5]
	v_cndmask_b32_e64 v28, v28, v30, s[4:5]
	v_pk_mul_f32 v[28:29], v[118:119], v[28:29] op_sel_hi:[0,1]
	v_cndmask_b32_e64 v69, v66, v69, s[6:7]
	v_pk_mul_f32 v[4:5], v[4:5], v[96:97] op_sel_hi:[1,0]
	s_waitcnt vmcnt(4)
	v_pk_fma_f32 v[28:29], v[48:49], v[28:29], v[60:61]
	v_pk_mul_f32 v[30:31], v[120:121], v[68:69] op_sel_hi:[0,1]
	v_pk_fma_f32 v[4:5], v[4:5], v[52:53], v[28:29]
	v_cndmask_b32_e64 v27, v26, v27, s[4:5]
	v_pk_fma_f32 v[4:5], v[56:57], v[30:31], v[4:5]
	v_cndmask_b32_e64 v26, v23, v25, s[4:5]
	v_mul_f32_e32 v28, 0xbfb8aa3b, v4
	v_exp_f32_e32 v28, v28
	v_mul_f32_e32 v25, 0xbfb8aa3b, v5
	v_exp_f32_e32 v25, v25
	v_pk_mul_f32 v[26:27], v[118:119], v[26:27] op_sel_hi:[0,1]
	v_add_f32_e32 v23, 1.0, v28
	v_rcp_f32_e32 v28, v23
	v_add_f32_e32 v23, 1.0, v25
	v_rcp_f32_e32 v29, v23
	v_pk_mul_f32 v[0:1], v[0:1], v[96:97] op_sel_hi:[1,0]
	s_waitcnt vmcnt(0)
	v_pk_fma_f32 v[26:27], v[32:33], v[26:27], v[44:45]
	v_pk_mul_f32 v[30:31], v[120:121], v[70:71] op_sel_hi:[0,1]
	v_pk_fma_f32 v[0:1], v[0:1], v[36:37], v[26:27]
	v_pk_mul_f32 v[4:5], v[4:5], v[28:29]
	v_pk_fma_f32 v[0:1], v[40:41], v[30:31], v[0:1]
	v_cndmask_b32_e64 v15, v15, v17, s[4:5]
	v_pk_mul_f32 v[0:1], v[0:1], v[4:5]
	v_cndmask_b32_e64 v4, v18, v20, s[6:7]
	v_cndmask_b32_e64 v18, v14, v16, s[6:7]
	v_cndmask_b32_e64 v14, v12, v13, s[4:5]
	v_pk_mul_f32 v[14:15], v[118:119], v[14:15] op_sel_hi:[0,1]
	v_cndmask_b32_e64 v19, v19, v21, s[6:7]
	v_pk_mul_f32 v[6:7], v[6:7], v[96:97] op_sel_hi:[1,0]
	v_pk_fma_f32 v[14:15], v[50:51], v[14:15], v[62:63]
	v_pk_mul_f32 v[12:13], v[120:121], v[18:19] op_sel_hi:[0,1]
	v_pk_fma_f32 v[6:7], v[6:7], v[54:55], v[14:15]
	v_cndmask_b32_e64 v11, v10, v11, s[4:5]
	v_pk_fma_f32 v[6:7], v[58:59], v[12:13], v[6:7]
	v_cndmask_b32_e64 v10, v8, v9, s[4:5]
	v_mul_f32_e32 v12, 0xbfb8aa3b, v6
	v_mul_f32_e32 v9, 0xbfb8aa3b, v7
	v_exp_f32_e32 v12, v12
	v_exp_f32_e32 v9, v9
	v_pk_mul_f32 v[10:11], v[118:119], v[10:11] op_sel_hi:[0,1]
	v_cndmask_b32_e64 v5, v22, v24, s[6:7]
	v_add_f32_e32 v8, 1.0, v12
	v_add_f32_e32 v9, 1.0, v9
	v_rcp_f32_e32 v8, v8
	v_rcp_f32_e32 v9, v9
	v_pk_mul_f32 v[2:3], v[2:3], v[96:97] op_sel_hi:[1,0]
	v_pk_fma_f32 v[10:11], v[34:35], v[10:11], v[46:47]
	v_pk_mul_f32 v[4:5], v[120:121], v[4:5] op_sel_hi:[0,1]
	v_pk_fma_f32 v[2:3], v[2:3], v[38:39], v[10:11]
	v_cvt_pk_bf16_f32 v0, v0, v1
	v_pk_fma_f32 v[2:3], v[42:43], v[4:5], v[2:3]
	v_pk_mul_f32 v[4:5], v[6:7], v[8:9]
	s_nop 0
	v_pk_mul_f32 v[2:3], v[2:3], v[4:5]
	s_nop 0
	v_cvt_pk_bf16_f32 v1, v2, v3
	v_mov_b64_e32 v[2:3], s[30:31]
	v_mad_i64_i32 v[2:3], s[4:5], v101, s1, v[2:3]
	v_lshl_add_u64 v[2:3], v[170:171], 1, v[2:3]
	v_mov_b32_e32 v178, v194
	v_mov_b32_e32 v179, v195
	v_mov_b32_e32 v180, v0
	v_mov_b32_e32 v181, v1
	global_store_dwordx4 v[2:3], v[178:181], off
